# v54 + prescale/final-norm wave_sum via DPP/permlane + SwiGLU epilogue: exponent argument acc*rn+sgn as one v_pk_fma_f32 instead of v_pk_mul + two v_add (54 sites)
# speedup vs baseline: 1.0015x; 1.0002x over previous
; __device__ __forceinline__ float wave_sum(float v) {
; #pragma unroll
;     for (int o = 1; o < 64; o <<= 1) v += __shfl_xor(v, o);
;     return v;
; }
; __device__ __forceinline__ void prescale_phase(const float* srcC, const float* srcL, const float* g, const float* modl, int iscale, bf16_t* U, unsigned long long* ssq, int gw, int ngw, int lane) {
;     ...
;         f32x4 x[8]; float ss = 0.f;
; #pragma unroll
;         for (int j = 0; j < 8; ++j) { x[j] = __builtin_nontemporal_load(xr + 64 * j); ss += (x[j].x * x[j].x + x[j].y * x[j].y) + (x[j].z * x[j].z + x[j].w * x[j].w); }
;         ss = wave_sum(ss);
;         if (lane == 0) ssq[m] = (unsigned long long)(ss * pg8::SSQ_SCALE);
;         u32x2* o = (u32x2*)(U + (size_t)m * DM) + lane;
; #pragma unroll
;         for (int j = 0; j < 8; ++j) { const f32x4 y = x[j] * cf[j];
;             u32x2 w; w.x = pk2(y.x, y.y); w.y = pk2(y.z, y.w); o[64 * j] = w; }
.LBB0_153:
	s_and_b64 s[10:11], s[40:41], exec
	s_cselect_b32 s11, s61, 0
	s_cselect_b32 s10, s60, s9
	s_cselect_b32 s9, s57, s35
	s_cselect_b32 s12, s56, s34
	s_lshl_b64 s[10:11], s[10:11], 13
	s_add_u32 s40, s12, s10
	s_addc_u32 s41, s9, s11
	v_lshl_add_u64 v[50:51], s[40:41], 0, v[174:175]
	s_movk_i32 s9, 0x1000
	v_add_co_u32_e32 v62, vcc, s9, v50
	s_nop 1
	v_addc_co_u32_e32 v63, vcc, 0, v51, vcc
	global_load_dwordx4 v[34:37], v174, s[40:41] nt
	global_load_dwordx4 v[38:41], v174, s[40:41] offset:1024 nt
	global_load_dwordx4 v[42:45], v174, s[40:41] offset:2048 nt
	global_load_dwordx4 v[46:49], v174, s[40:41] offset:3072 nt
	global_load_dwordx4 v[50:53], v[62:63], off nt
	global_load_dwordx4 v[54:57], v[62:63], off offset:1024 nt
	global_load_dwordx4 v[58:61], v[62:63], off offset:2048 nt
	global_load_dwordx4 v[62:65], v[62:63], off offset:3072 nt
	s_waitcnt vmcnt(7)
	v_mul_f32_e32 v85, v35, v35
	v_mul_f32_e32 v86, v37, v37
	v_fmac_f32_e32 v85, v34, v34
	v_fmac_f32_e32 v86, v36, v36
	v_add_f32_e32 v84, v85, v86
	s_waitcnt vmcnt(6)
	v_mul_f32_e32 v85, v39, v39
	v_mul_f32_e32 v86, v41, v41
	v_fmac_f32_e32 v85, v38, v38
	v_fmac_f32_e32 v86, v40, v40
	v_add_f32_e32 v85, v85, v86
	v_add_f32_e32 v84, v84, v85
	s_waitcnt vmcnt(5)
	v_mul_f32_e32 v85, v43, v43
	v_mul_f32_e32 v86, v45, v45
	v_fmac_f32_e32 v85, v42, v42
	v_fmac_f32_e32 v86, v44, v44
	v_add_f32_e32 v85, v85, v86
	v_add_f32_e32 v84, v84, v85
	s_waitcnt vmcnt(4)
	v_mul_f32_e32 v85, v47, v47
	v_mul_f32_e32 v86, v49, v49
	v_fmac_f32_e32 v85, v46, v46
	v_fmac_f32_e32 v86, v48, v48
	v_add_f32_e32 v85, v85, v86
	v_add_f32_e32 v84, v84, v85
	s_waitcnt vmcnt(3)
	v_mul_f32_e32 v85, v51, v51
	v_mul_f32_e32 v86, v53, v53
	v_fmac_f32_e32 v85, v50, v50
	v_fmac_f32_e32 v86, v52, v52
	v_add_f32_e32 v85, v85, v86
	v_add_f32_e32 v84, v84, v85
	s_waitcnt vmcnt(2)
	v_mul_f32_e32 v85, v55, v55
	v_mul_f32_e32 v86, v57, v57
	v_fmac_f32_e32 v85, v54, v54
	v_fmac_f32_e32 v86, v56, v56
	v_add_f32_e32 v85, v85, v86
	v_add_f32_e32 v84, v84, v85
	s_waitcnt vmcnt(1)
	v_mul_f32_e32 v85, v59, v59
	v_mul_f32_e32 v86, v61, v61
	v_fmac_f32_e32 v85, v58, v58
	v_fmac_f32_e32 v86, v60, v60
	v_add_f32_e32 v85, v85, v86
	v_add_f32_e32 v84, v84, v85
	s_waitcnt vmcnt(0)
	v_mul_f32_e32 v85, v63, v63
	v_mul_f32_e32 v86, v65, v65
	v_fmac_f32_e32 v85, v62, v62
	v_fmac_f32_e32 v86, v64, v64
	v_add_f32_e32 v85, v85, v86
	v_add_f32_e32 v84, v84, v85
	s_waitcnt lgkmcnt(0)
	s_nop 1
	v_add_f32_dpp v84, v84, v84 quad_perm:[1,0,3,2] row_mask:0xf bank_mask:0xf
	s_waitcnt lgkmcnt(0)
	s_nop 1
	v_add_f32_dpp v84, v84, v84 quad_perm:[2,3,0,1] row_mask:0xf bank_mask:0xf
	s_waitcnt lgkmcnt(0)
	s_nop 1
	v_add_f32_dpp v84, v84, v84 row_half_mirror row_mask:0xf bank_mask:0xf
	s_waitcnt lgkmcnt(0)
	s_nop 1
	v_add_f32_dpp v84, v84, v84 row_mirror row_mask:0xf bank_mask:0xf
	v_mov_b32_e32 v85, v84
	s_nop 1
	v_permlane16_swap_b32 v84, v85
	s_waitcnt lgkmcnt(0)
	v_add_f32_e32 v84, v84, v85
	v_mov_b32_e32 v85, v84
	s_nop 1
	v_permlane32_swap_b32 v84, v85
	s_and_saveexec_b64 s[40:41], s[38:39]
	s_cbranch_execz .LBB0_150
	s_waitcnt lgkmcnt(0)
	v_add_f32_e32 v84, v84, v85
	v_mul_f32_e32 v84, 0x49800000, v84
	v_trunc_f32_e32 v84, v84
	v_mul_f32_e32 v85, 0x2f800000, v84
	v_floor_f32_e32 v85, v85
	v_fmac_f32_e32 v84, 0xcf800000, v85
	v_cvt_u32_f32_e32 v84, v84
	v_cvt_u32_f32_e32 v85, v85
	s_add_u32 s10, s58, s5
	s_addc_u32 s11, s59, s7
	global_store_dwordx2 v175, v[84:85], s[10:11]
	s_branch .LBB0_150

; __device__ __forceinline__ void row_rstd(const unsigned long long* ssq, int row0, float (&rs)[2][4]) {
;     unsigned long long q[2][4];
; #pragma unroll
;     for (int ai = 0; ai < 2; ++ai)
; #pragma unroll
;         for (int m = 0; m < 4; ++m) q[ai][m] = ssq[row0 + ai * HALF + m * 16];
;     asm volatile("" : "+v"(q[0][0]), "+v"(q[0][1]), "+v"(q[0][2]), "+v"(q[0][3]), "+v"(q[1][0]), "+v"(q[1][1]), "+v"(q[1][2]), "+v"(q[1][3]));
; #pragma unroll
;     for (int ai = 0; ai < 2; ++ai)
; #pragma unroll
;         for (int m = 0; m < 4; ++m) {
;             const float qf = __builtin_fmaf((float)(unsigned)(q[ai][m] >> 32), 4294967296.0f, (float)(unsigned)q[ai][m]);
;             rs[ai][m] = __builtin_amdgcn_rsqf(__builtin_fmaf(qf, 1.0f / (SSQ_SCALE * DM), EPS)); }
; }
;     template <int QVV> __device__ __forceinline__ void run(f32x4 (&acc)[2][2][4][2], const Unit& u, int wr, int wc, int fr, int fq) const {
;         constexpr int nai = (QVV == 2) ? 1 : 2; const int r0 = u.pm * BM + (QVV == 2 ? (u.seg - 1) * HALF : 0);
;         char* tb = (char*)(O + (size_t)r0 * DFF + u.pn * HALF);
;         const int v = u.pm < 4 ? 4 : ((u.pm - 4) >> 5);
;         const char* swb = (const char*)(sw + (size_t)v * SWLD + u.pn * BM);
;         unsigned lo = (unsigned)((wr * 64 + fr) * DFF + wc * 32 + 8 * fq) * 2u;
;         unsigned co = (unsigned)(wc * 32 + 8 * fq) * 4u;
;         asm volatile("" : "+v"(lo), "+v"(co));
;         float rs[2][4]; row_rstd(ssq, r0 + wr * 64 + fr, rs);
;         f32x4 sg[2], su[2], sgn[2];
; #pragma unroll
;         for (int n = 0; n < 2; ++n) { sg[n] = *(const f32x4*)(swb + co + n * 16); su[n] = *(const f32x4*)(swb + co + HALF * 4 + n * 16); sgn[n] = sg[n] * (-LOG2E); }
.LBB0_228:
	s_lshl_b32 s30, s49, 8
	v_add_u32_e32 v82, s30, v169
	v_ashrrev_i32_e32 v83, 31, v82
	v_mov_b32_e32 v166, v170
	v_mov_b32_e32 v98, v171
	v_lshl_add_u64 v[82:83], v[82:83], 3, s[34:35]
	global_load_dwordx2 v[150:151], v[82:83], off
	global_load_dwordx2 v[152:153], v[82:83], off offset:128
	global_load_dwordx2 v[154:155], v[82:83], off offset:256
	global_load_dwordx2 v[156:157], v[82:83], off offset:384
	global_load_dwordx2 v[178:179], v[82:83], off offset:1024
	global_load_dwordx2 v[180:181], v[82:83], off offset:1152
	global_load_dwordx2 v[182:183], v[82:83], off offset:1280
	global_load_dwordx2 v[184:185], v[82:83], off offset:1408
	s_mul_i32 s31, s49, 0x2b0000
	s_mul_hi_i32 s30, s30, 0x2b00
	s_add_u32 s49, s5, s31
	s_addc_u32 s50, s7, s30
	s_lshl_b32 s30, s48, 7
	s_ashr_i32 s31, s30, 31
	s_lshl_b64 s[30:31], s[30:31], 1
	s_add_u32 s30, s49, s30
	s_addc_u32 s31, s50, s31
	s_lshl_b64 s[42:43], s[42:43], 2
	s_add_u32 s49, s2, s42
	s_addc_u32 s50, s3, s43
	s_lshl_b32 s42, s48, 8
	s_ashr_i32 s43, s42, 31
	s_lshl_b64 s[42:43], s[42:43], 2
	s_add_u32 s42, s49, s42
	s_addc_u32 s43, s50, s43
	s_flbit_i32_b32 s48, 0
	s_min_u32 s48, s48, 32
	s_sub_i32 s49, 32, s48
	v_mov_b32_e32 v167, v175
	v_lshl_add_u64 v[146:147], s[30:31], 0, v[166:167]
	s_waitcnt vmcnt(0)
	global_load_dwordx4 v[86:89], v98, s[42:43] offset:16
	global_load_dwordx4 v[102:105], v98, s[42:43]
	global_load_dwordx4 v[82:85], v98, s[42:43] offset:528
	s_nop 0
	global_load_dwordx4 v[98:101], v98, s[42:43] offset:512
	v_mov_b32_e32 v174, v151
	v_cvt_f32_u32_e32 v148, v150
	v_lshlrev_b64 v[150:151], s48, v[174:175]
	v_mov_b32_e32 v174, v153
	v_cvt_f32_u32_e32 v158, v152
	v_min_u32_e32 v150, 1, v150
	v_lshlrev_b64 v[152:153], s48, v[174:175]
	v_mov_b32_e32 v174, v155
	v_or_b32_e32 v155, v151, v150
	v_min_u32_e32 v152, 1, v152
	v_lshlrev_b64 v[150:151], s48, v[174:175]
	v_mov_b32_e32 v174, v157
	v_cvt_f32_u32_e32 v155, v155
	v_or_b32_e32 v157, v153, v152
	v_min_u32_e32 v150, 1, v150
	v_lshlrev_b64 v[152:153], s48, v[174:175]
	v_mov_b32_e32 v174, v179
	v_cvt_f32_u32_e32 v157, v157
	v_or_b32_e32 v162, v151, v150
	v_min_u32_e32 v152, 1, v152
	v_lshlrev_b64 v[150:151], s48, v[174:175]
	v_mov_b32_e32 v174, v181
	v_cvt_f32_u32_e32 v162, v162
	v_or_b32_e32 v164, v153, v152
	v_min_u32_e32 v150, 1, v150
	v_lshlrev_b64 v[152:153], s48, v[174:175]
	v_mov_b32_e32 v174, v183
	v_cvt_f32_u32_e32 v154, v154
	v_cvt_f32_u32_e32 v164, v164
	v_or_b32_e32 v168, v151, v150
	v_lshlrev_b64 v[150:151], s48, v[174:175]
	v_cvt_f32_u32_e32 v156, v156
	v_min_u32_e32 v152, 1, v152
	v_mov_b32_e32 v174, v185
	v_ldexp_f32 v155, v155, s49
	v_cvt_f32_u32_e32 v168, v168
	v_min_u32_e32 v150, 1, v150
	v_cvt_f32_u32_e32 v160, v178
	v_or_b32_e32 v178, v153, v152
	v_lshlrev_b64 v[152:153], s48, v[174:175]
	v_fmac_f32_e32 v148, 0x4f800000, v155
	v_ldexp_f32 v155, v157, s49
	v_or_b32_e32 v150, v151, v150
	v_cvt_f32_u32_e32 v157, v178
	v_min_u32_e32 v151, 1, v152
	v_fmamk_f32 v148, v148, 0x30000000, v231
	v_fmac_f32_e32 v158, 0x4f800000, v155
	v_ldexp_f32 v152, v162, s49
	v_cvt_f32_u32_e32 v150, v150
	v_cvt_f32_u32_e32 v167, v180
	v_cvt_f32_u32_e32 v177, v182
	v_or_b32_e32 v151, v153, v151
	v_rsq_f32_e32 v174, v148
	v_fmamk_f32 v148, v158, 0x30000000, v231
	v_fmac_f32_e32 v154, 0x4f800000, v152
	v_ldexp_f32 v152, v164, s49
	v_cvt_f32_u32_e32 v151, v151
	v_rsq_f32_e32 v178, v148
	v_fmamk_f32 v148, v154, 0x30000000, v231
	v_fmac_f32_e32 v156, 0x4f800000, v152
	v_ldexp_f32 v152, v168, s49
	v_cvt_f32_u32_e32 v188, v184
	v_rsq_f32_e32 v168, v148
	v_fmamk_f32 v148, v156, 0x30000000, v231
	v_fmac_f32_e32 v160, 0x4f800000, v152
	v_ldexp_f32 v152, v157, s49
	v_rsq_f32_e32 v164, v148
	v_fmamk_f32 v148, v160, 0x30000000, v231
	v_ldexp_f32 v150, v150, s49
	v_fmac_f32_e32 v167, 0x4f800000, v152
	v_rsq_f32_e32 v162, v148
	v_fmac_f32_e32 v177, 0x4f800000, v150
	v_mul_f32_e32 v148, 0xbfb8aa3b, v174
	s_mov_b32 s42, 0xbfb8aa3b
	v_fmamk_f32 v152, v167, 0x30000000, v231
	v_ldexp_f32 v150, v151, s49
	v_fmamk_f32 v151, v177, 0x30000000, v231
	v_pk_mul_f32 v[182:183], v[142:143], v[148:149] op_sel_hi:[1,0]
	s_waitcnt vmcnt(2)
	v_pk_mul_f32 v[156:157], v[102:103], s[42:43] op_sel_hi:[1,0]
	v_rsq_f32_e32 v160, v152
	v_fmac_f32_e32 v188, 0x4f800000, v150
	v_pk_mul_f32 v[180:181], v[144:145], v[148:149] op_sel_hi:[1,0]
	v_pk_mul_f32 v[184:185], v[136:137], v[148:149] op_sel_hi:[1,0]
	v_pk_mul_f32 v[186:187], v[134:135], v[148:149] op_sel_hi:[1,0]
	v_rsq_f32_e32 v158, v151
	v_pk_mul_f32 v[154:155], v[104:105], s[42:43] op_sel_hi:[1,0]
	v_pk_mul_f32 v[150:151], v[88:89], s[42:43] op_sel_hi:[1,0]
	v_pk_mul_f32 v[152:153], v[86:87], s[42:43] op_sel_hi:[1,0]
	v_pk_fma_f32 v[144:145], v[144:145], v[174:175], v[104:105] op_sel_hi:[1,0,1]
	v_pk_fma_f32 v[142:143], v[142:143], v[174:175], v[102:103] op_sel_hi:[1,0,1]
	s_waitcnt vmcnt(0)
;     template <int QVV> __device__ __forceinline__ void run(f32x4 (&acc)[2][2][4][2], const Unit& u, int wr, int wc, int fr, int fq) const {
;     ...
;             for (int m = 0; m < 4; ++m) { if (ai >= nai) continue;
;                 const float r = rs[ai][m], rn = r * (-LOG2E);
;                 f32x4 o[2];
; #pragma unroll
;                 for (int n = 0; n < 2; ++n) {
;                     const f32x4 gt = acc[ai][0][m][n] * r + sg[n], up = acc[ai][1][m][n] * r + su[n], ex = acc[ai][0][m][n] * rn + sgn[n];
;                     f32x4 den, rc;
; #pragma unroll
;                     for (int i = 0; i < 4; ++i) den[i] = __builtin_amdgcn_exp2f(ex[i]);
;                     den = den + 1.0f;
; #pragma unroll
;                     for (int i = 0; i < 4; ++i) rc[i] = __builtin_amdgcn_rcpf(den[i]);
;                     o[n] = (gt * up) * rc; }
;                 u32x4 w; w.x = pk2(o[0][0], o[0][1]); w.y = pk2(o[0][2], o[0][3]); w.z = pk2(o[1][0], o[1][1]); w.w = pk2(o[1][2], o[1][3]);
;                 *(u32x4*)(tb + lo + (unsigned)(ai * HALF + m * 16) * (DFF * 2)) = w; }
	v_pk_fma_f32 v[140:141], v[140:141], v[174:175], v[100:101] op_sel_hi:[1,0,1]
	v_pk_fma_f32 v[138:139], v[138:139], v[174:175], v[98:99] op_sel_hi:[1,0,1]
	v_pk_fma_f32 v[136:137], v[136:137], v[174:175], v[88:89] op_sel_hi:[1,0,1]
	v_pk_fma_f32 v[134:135], v[134:135], v[174:175], v[86:87] op_sel_hi:[1,0,1]
	v_pk_fma_f32 v[132:133], v[132:133], v[174:175], v[84:85] op_sel_hi:[1,0,1]
	v_pk_fma_f32 v[130:131], v[130:131], v[174:175], v[82:83] op_sel_hi:[1,0,1]
	v_add_f32_e32 v167, v156, v182
	v_add_f32_e32 v174, v157, v183
	v_add_f32_e32 v177, v154, v180
	v_add_f32_e32 v179, v155, v181
	v_pk_mul_f32 v[138:139], v[142:143], v[138:139]
	v_pk_mul_f32 v[140:141], v[144:145], v[140:141]
	v_add_f32_e32 v142, v152, v186
	v_add_f32_e32 v143, v153, v187
	v_add_f32_e32 v144, v150, v184
	v_add_f32_e32 v145, v151, v185
	v_pk_mul_f32 v[130:131], v[134:135], v[130:131]
	v_exp_f32_e32 v134, v167
	v_exp_f32_e32 v135, v174
	v_pk_mul_f32 v[132:133], v[136:137], v[132:133]
	v_exp_f32_e32 v136, v177
	v_exp_f32_e32 v137, v179
	v_exp_f32_e32 v142, v142
	v_exp_f32_e32 v144, v144
	v_exp_f32_e32 v145, v145
	v_exp_f32_e32 v143, v143
	v_pk_add_f32 v[134:135], v[134:135], 1.0 op_sel_hi:[1,0]
	v_pk_add_f32 v[136:137], v[136:137], 1.0 op_sel_hi:[1,0]
	v_pk_add_f32 v[144:145], v[144:145], 1.0 op_sel_hi:[1,0]
	v_pk_add_f32 v[142:143], v[142:143], 1.0 op_sel_hi:[1,0]
	v_rcp_f32_e32 v134, v134
	v_rcp_f32_e32 v135, v135
	v_rcp_f32_e32 v136, v136
	v_rcp_f32_e32 v137, v137
	v_rcp_f32_e32 v142, v142
	v_rcp_f32_e32 v144, v144
	v_rcp_f32_e32 v145, v145
	v_rcp_f32_e32 v143, v143
	v_pk_mul_f32 v[134:135], v[138:139], v[134:135]
	v_pk_mul_f32 v[136:137], v[140:141], v[136:137]
	v_pk_mul_f32 v[138:139], v[132:133], v[144:145]
	v_pk_mul_f32 v[132:133], v[130:131], v[142:143]
	v_cvt_pk_bf16_f32 v130, v134, v135
	v_mul_f32_e32 v134, 0xbfb8aa3b, v178
	v_cvt_pk_bf16_f32 v131, v136, v137
	v_pk_mul_f32 v[136:137], v[128:129], v[134:135] op_sel_hi:[1,0]
	v_pk_fma_f32 v[140:141], v[126:127], v[134:135], v[156:157] op_sel_hi:[1,0,1]
	v_add_f32_e32 v135, v154, v136
	v_exp_f32_e32 v136, v135
	v_add_f32_e32 v135, v155, v137
	v_pk_fma_f32 v[128:129], v[128:129], v[178:179], v[104:105] op_sel_hi:[1,0,1]
	v_pk_fma_f32 v[126:127], v[126:127], v[178:179], v[102:103] op_sel_hi:[1,0,1]
	v_pk_fma_f32 v[124:125], v[124:125], v[178:179], v[100:101] op_sel_hi:[1,0,1]
	v_pk_fma_f32 v[122:123], v[122:123], v[178:179], v[98:99] op_sel_hi:[1,0,1]
	v_pk_mul_f32 v[124:125], v[128:129], v[124:125]
	v_pk_mul_f32 v[122:123], v[126:127], v[122:123]
	v_pk_fma_f32 v[126:127], v[120:121], v[134:135], v[150:151] op_sel_hi:[1,0,1]
	v_pk_fma_f32 v[128:129], v[118:119], v[134:135], v[152:153] op_sel_hi:[1,0,1]
	v_cvt_pk_bf16_f32 v132, v132, v133
	v_exp_f32_e32 v140, v140
	v_exp_f32_e32 v128, v128
	v_exp_f32_e32 v126, v126
	v_exp_f32_e32 v127, v127
	v_exp_f32_e32 v129, v129
	v_exp_f32_e32 v141, v141
	v_cvt_pk_bf16_f32 v133, v138, v139
	v_pk_add_f32 v[126:127], v[126:127], 1.0 op_sel_hi:[1,0]
	v_pk_add_f32 v[128:129], v[128:129], 1.0 op_sel_hi:[1,0]
	global_store_dwordx4 v166, v[130:133], s[30:31]
	v_rcp_f32_e32 v128, v128
	v_rcp_f32_e32 v129, v129
	v_pk_add_f32 v[132:133], v[140:141], 1.0 op_sel_hi:[1,0]
	v_rcp_f32_e32 v126, v126
	v_rcp_f32_e32 v127, v127
	v_rcp_f32_e32 v132, v132
	v_rcp_f32_e32 v133, v133
	v_pk_fma_f32 v[120:121], v[120:121], v[178:179], v[88:89] op_sel_hi:[1,0,1]
	v_pk_fma_f32 v[118:119], v[118:119], v[178:179], v[86:87] op_sel_hi:[1,0,1]
	v_pk_fma_f32 v[116:117], v[116:117], v[178:179], v[84:85] op_sel_hi:[1,0,1]
	v_pk_fma_f32 v[114:115], v[114:115], v[178:179], v[82:83] op_sel_hi:[1,0,1]
	v_pk_mul_f32 v[116:117], v[120:121], v[116:117]
	v_pk_mul_f32 v[114:115], v[118:119], v[114:115]
	v_pk_mul_f32 v[118:119], v[116:117], v[126:127]
	v_pk_mul_f32 v[116:117], v[114:115], v[128:129]
	v_pk_mul_f32 v[122:123], v[122:123], v[132:133]
	v_cvt_pk_bf16_f32 v116, v116, v117
	v_cvt_pk_bf16_f32 v117, v118, v119
	v_mul_f32_e32 v118, 0xbfb8aa3b, v168
	v_exp_f32_e32 v137, v135
	v_cvt_pk_bf16_f32 v114, v122, v123
	v_pk_fma_f32 v[122:123], v[110:111], v[118:119], v[156:157] op_sel_hi:[1,0,1]
	v_pk_mul_f32 v[120:121], v[112:113], v[118:119] op_sel_hi:[1,0]
	v_exp_f32_e32 v122, v122
	v_exp_f32_e32 v123, v123
	v_add_f32_e32 v119, v154, v120
	v_pk_add_f32 v[130:131], v[136:137], 1.0 op_sel_hi:[1,0]
	v_exp_f32_e32 v120, v119
	v_add_f32_e32 v119, v155, v121
	v_pk_fma_f32 v[112:113], v[112:113], v[168:169], v[104:105] op_sel_hi:[1,0,1]
	v_pk_fma_f32 v[110:111], v[110:111], v[168:169], v[102:103] op_sel_hi:[1,0,1]
	v_pk_fma_f32 v[108:109], v[108:109], v[168:169], v[100:101] op_sel_hi:[1,0,1]
	v_pk_fma_f32 v[106:107], v[106:107], v[168:169], v[98:99] op_sel_hi:[1,0,1]
	v_rcp_f32_e32 v130, v130
	v_rcp_f32_e32 v131, v131
	v_pk_mul_f32 v[106:107], v[110:111], v[106:107]
	v_pk_mul_f32 v[108:109], v[112:113], v[108:109]
	v_pk_fma_f32 v[110:111], v[96:97], v[118:119], v[150:151] op_sel_hi:[1,0,1]
	v_pk_fma_f32 v[112:113], v[94:95], v[118:119], v[152:153] op_sel_hi:[1,0,1]
	v_exp_f32_e32 v112, v112
	v_exp_f32_e32 v110, v110
	v_exp_f32_e32 v111, v111
	v_exp_f32_e32 v113, v113
	v_pk_mul_f32 v[124:125], v[124:125], v[130:131]
	s_mov_b32 s30, 0x2b000
	v_cvt_pk_bf16_f32 v115, v124, v125
	v_add_co_u32_e32 v124, vcc, s30, v146
	v_pk_add_f32 v[110:111], v[110:111], 1.0 op_sel_hi:[1,0]
	s_nop 0
	v_addc_co_u32_e32 v125, vcc, 0, v147, vcc
	v_pk_add_f32 v[112:113], v[112:113], 1.0 op_sel_hi:[1,0]
	global_store_dwordx4 v[124:125], v[114:117], off
	v_rcp_f32_e32 v112, v112
	v_rcp_f32_e32 v113, v113
	v_pk_add_f32 v[116:117], v[122:123], 1.0 op_sel_hi:[1,0]
	v_rcp_f32_e32 v110, v110
	v_rcp_f32_e32 v111, v111
	v_rcp_f32_e32 v116, v116
	v_rcp_f32_e32 v117, v117
;     template <int QVV> __device__ __forceinline__ void run(f32x4 (&acc)[2][2][4][2], const Unit& u, int wr, int wc, int fr, int fq) const {
;     ...
;             for (int m = 0; m < 4; ++m) { if (ai >= nai) continue;
;                 const float r = rs[ai][m], rn = r * (-LOG2E);
;                 f32x4 o[2];
; #pragma unroll
;                 for (int n = 0; n < 2; ++n) {
;                     const f32x4 gt = acc[ai][0][m][n] * r + sg[n], up = acc[ai][1][m][n] * r + su[n], ex = acc[ai][0][m][n] * rn + sgn[n];
;                     f32x4 den, rc;
; #pragma unroll
;                     for (int i = 0; i < 4; ++i) den[i] = __builtin_amdgcn_exp2f(ex[i]);
;                     den = den + 1.0f;
; #pragma unroll
;                     for (int i = 0; i < 4; ++i) rc[i] = __builtin_amdgcn_rcpf(den[i]);
;                     o[n] = (gt * up) * rc; }
;                 u32x4 w; w.x = pk2(o[0][0], o[0][1]); w.y = pk2(o[0][2], o[0][3]); w.z = pk2(o[1][0], o[1][1]); w.w = pk2(o[1][2], o[1][3]);
;                 *(u32x4*)(tb + lo + (unsigned)(ai * HALF + m * 16) * (DFF * 2)) = w; }
	v_pk_fma_f32 v[96:97], v[96:97], v[168:169], v[88:89] op_sel_hi:[1,0,1]
	v_pk_fma_f32 v[94:95], v[94:95], v[168:169], v[86:87] op_sel_hi:[1,0,1]
	v_pk_fma_f32 v[92:93], v[92:93], v[168:169], v[84:85] op_sel_hi:[1,0,1]
	v_pk_fma_f32 v[90:91], v[90:91], v[168:169], v[82:83] op_sel_hi:[1,0,1]
	v_pk_mul_f32 v[92:93], v[96:97], v[92:93]
	v_pk_mul_f32 v[90:91], v[94:95], v[90:91]
	v_pk_mul_f32 v[94:95], v[92:93], v[110:111]
	v_pk_mul_f32 v[92:93], v[90:91], v[112:113]
	v_pk_mul_f32 v[106:107], v[106:107], v[116:117]
	v_cvt_pk_bf16_f32 v92, v92, v93
	v_cvt_pk_bf16_f32 v93, v94, v95
	v_mul_f32_e32 v94, 0xbfb8aa3b, v164
	v_exp_f32_e32 v121, v119
	v_cvt_pk_bf16_f32 v90, v106, v107
	v_pk_fma_f32 v[106:107], v[78:79], v[94:95], v[156:157] op_sel_hi:[1,0,1]
	v_pk_mul_f32 v[96:97], v[80:81], v[94:95] op_sel_hi:[1,0]
	v_exp_f32_e32 v106, v106
	v_exp_f32_e32 v107, v107
	v_add_f32_e32 v95, v154, v96
	v_pk_add_f32 v[114:115], v[120:121], 1.0 op_sel_hi:[1,0]
	v_exp_f32_e32 v96, v95
	v_add_f32_e32 v95, v155, v97
	v_pk_fma_f32 v[80:81], v[80:81], v[164:165], v[104:105] op_sel_hi:[1,0,1]
	v_pk_fma_f32 v[78:79], v[78:79], v[164:165], v[102:103] op_sel_hi:[1,0,1]
	v_pk_fma_f32 v[76:77], v[76:77], v[164:165], v[100:101] op_sel_hi:[1,0,1]
	v_pk_fma_f32 v[74:75], v[74:75], v[164:165], v[98:99] op_sel_hi:[1,0,1]
	v_rcp_f32_e32 v114, v114
	v_rcp_f32_e32 v115, v115
	v_pk_mul_f32 v[74:75], v[78:79], v[74:75]
	v_pk_mul_f32 v[76:77], v[80:81], v[76:77]
	v_pk_fma_f32 v[78:79], v[72:73], v[94:95], v[150:151] op_sel_hi:[1,0,1]
	v_pk_fma_f32 v[80:81], v[70:71], v[94:95], v[152:153] op_sel_hi:[1,0,1]
	v_exp_f32_e32 v80, v80
	v_exp_f32_e32 v78, v78
	v_exp_f32_e32 v79, v79
	v_exp_f32_e32 v81, v81
	v_pk_mul_f32 v[108:109], v[108:109], v[114:115]
	s_mov_b32 s30, 0x56000
	v_cvt_pk_bf16_f32 v91, v108, v109
	v_add_co_u32_e32 v108, vcc, s30, v146
	v_pk_add_f32 v[78:79], v[78:79], 1.0 op_sel_hi:[1,0]
	s_nop 0
	v_addc_co_u32_e32 v109, vcc, 0, v147, vcc
	v_pk_add_f32 v[80:81], v[80:81], 1.0 op_sel_hi:[1,0]
	global_store_dwordx4 v[108:109], v[90:93], off
	v_rcp_f32_e32 v80, v80
	v_rcp_f32_e32 v81, v81
	v_pk_add_f32 v[92:93], v[106:107], 1.0 op_sel_hi:[1,0]
	v_rcp_f32_e32 v78, v78
	v_rcp_f32_e32 v79, v79
	v_rcp_f32_e32 v92, v92
	v_rcp_f32_e32 v93, v93
	v_pk_fma_f32 v[72:73], v[72:73], v[164:165], v[88:89] op_sel_hi:[1,0,1]
	v_pk_fma_f32 v[70:71], v[70:71], v[164:165], v[86:87] op_sel_hi:[1,0,1]
	v_pk_fma_f32 v[68:69], v[68:69], v[164:165], v[84:85] op_sel_hi:[1,0,1]
	v_pk_fma_f32 v[66:67], v[66:67], v[164:165], v[82:83] op_sel_hi:[1,0,1]
	v_pk_mul_f32 v[68:69], v[72:73], v[68:69]
	v_pk_mul_f32 v[66:67], v[70:71], v[66:67]
	v_pk_mul_f32 v[70:71], v[68:69], v[78:79]
	v_pk_mul_f32 v[68:69], v[66:67], v[80:81]
	v_pk_mul_f32 v[74:75], v[74:75], v[92:93]
	v_cvt_pk_bf16_f32 v68, v68, v69
	v_cvt_pk_bf16_f32 v69, v70, v71
	v_mul_f32_e32 v70, 0xbfb8aa3b, v162
	v_exp_f32_e32 v97, v95
	v_cvt_pk_bf16_f32 v66, v74, v75
	v_pk_fma_f32 v[74:75], v[62:63], v[70:71], v[156:157] op_sel_hi:[1,0,1]
	v_pk_mul_f32 v[72:73], v[64:65], v[70:71] op_sel_hi:[1,0]
	v_exp_f32_e32 v74, v74
	v_exp_f32_e32 v75, v75
	v_add_f32_e32 v71, v154, v72
	v_pk_add_f32 v[90:91], v[96:97], 1.0 op_sel_hi:[1,0]
	v_exp_f32_e32 v72, v71
	v_add_f32_e32 v71, v155, v73
	v_pk_fma_f32 v[64:65], v[64:65], v[162:163], v[104:105] op_sel_hi:[1,0,1]
	v_pk_fma_f32 v[62:63], v[62:63], v[162:163], v[102:103] op_sel_hi:[1,0,1]
	v_pk_fma_f32 v[60:61], v[60:61], v[162:163], v[100:101] op_sel_hi:[1,0,1]
	v_pk_fma_f32 v[58:59], v[58:59], v[162:163], v[98:99] op_sel_hi:[1,0,1]
	v_rcp_f32_e32 v90, v90
	v_rcp_f32_e32 v91, v91
	v_pk_mul_f32 v[58:59], v[62:63], v[58:59]
	v_pk_mul_f32 v[60:61], v[64:65], v[60:61]
	v_pk_fma_f32 v[62:63], v[56:57], v[70:71], v[150:151] op_sel_hi:[1,0,1]
	v_pk_fma_f32 v[64:65], v[54:55], v[70:71], v[152:153] op_sel_hi:[1,0,1]
	v_exp_f32_e32 v64, v64
	v_exp_f32_e32 v62, v62
	v_exp_f32_e32 v63, v63
	v_exp_f32_e32 v65, v65
	v_pk_mul_f32 v[76:77], v[76:77], v[90:91]
	s_mov_b32 s30, 0x81000
	v_cvt_pk_bf16_f32 v67, v76, v77
	v_add_co_u32_e32 v76, vcc, s30, v146
	v_pk_add_f32 v[62:63], v[62:63], 1.0 op_sel_hi:[1,0]
	s_nop 0
	v_addc_co_u32_e32 v77, vcc, 0, v147, vcc
	v_pk_add_f32 v[64:65], v[64:65], 1.0 op_sel_hi:[1,0]
	global_store_dwordx4 v[76:77], v[66:69], off
	v_rcp_f32_e32 v64, v64
	v_rcp_f32_e32 v65, v65
	v_pk_add_f32 v[68:69], v[74:75], 1.0 op_sel_hi:[1,0]
	v_rcp_f32_e32 v62, v62
	v_rcp_f32_e32 v63, v63
	v_rcp_f32_e32 v68, v68
	v_rcp_f32_e32 v69, v69
	v_pk_fma_f32 v[56:57], v[56:57], v[162:163], v[88:89] op_sel_hi:[1,0,1]
	v_pk_fma_f32 v[54:55], v[54:55], v[162:163], v[86:87] op_sel_hi:[1,0,1]
	v_pk_fma_f32 v[52:53], v[52:53], v[162:163], v[84:85] op_sel_hi:[1,0,1]
	v_pk_fma_f32 v[50:51], v[50:51], v[162:163], v[82:83] op_sel_hi:[1,0,1]
	v_pk_mul_f32 v[52:53], v[56:57], v[52:53]
	v_pk_mul_f32 v[50:51], v[54:55], v[50:51]
	v_pk_mul_f32 v[54:55], v[52:53], v[62:63]
	v_pk_mul_f32 v[52:53], v[50:51], v[64:65]
	v_pk_mul_f32 v[58:59], v[58:59], v[68:69]
	v_cvt_pk_bf16_f32 v52, v52, v53
	v_cvt_pk_bf16_f32 v53, v54, v55
	v_mul_f32_e32 v54, 0xbfb8aa3b, v160
	v_exp_f32_e32 v73, v71
	v_cvt_pk_bf16_f32 v50, v58, v59
	v_pk_fma_f32 v[58:59], v[46:47], v[54:55], v[156:157] op_sel_hi:[1,0,1]
	v_pk_mul_f32 v[56:57], v[48:49], v[54:55] op_sel_hi:[1,0]
	v_exp_f32_e32 v58, v58
	v_exp_f32_e32 v59, v59
	v_add_f32_e32 v55, v154, v56
	v_pk_add_f32 v[66:67], v[72:73], 1.0 op_sel_hi:[1,0]
	v_exp_f32_e32 v56, v55
	v_add_f32_e32 v55, v155, v57
	v_pk_fma_f32 v[48:49], v[48:49], v[160:161], v[104:105] op_sel_hi:[1,0,1]
	v_pk_fma_f32 v[46:47], v[46:47], v[160:161], v[102:103] op_sel_hi:[1,0,1]
	v_pk_fma_f32 v[44:45], v[44:45], v[160:161], v[100:101] op_sel_hi:[1,0,1]
; #define PG8_BAR __builtin_amdgcn_s_barrier()
;     ...
;         if (wr == 0) PG8_BAR;
;         E.template run<QV>(acc, cur, wr, wc, fr, fq);
;         if (!has_next) break;
;         if (!cur.keep) {
; #pragma unroll
;             for (int a = 0; a < 2; ++a)
; #pragma unroll
;                 for (int b = 0; b < 2; ++b)
; #pragma unroll
;                     for (int m = 0; m < 4; ++m)
; #pragma unroll
;                         for (int n = 0; n < 2; ++n) { f32x2 z0, z1; asm("v_mov_b64 %0, 0\n\tv_mov_b64 %1, 0" : "=v"(z0), "=v"(z1));
;                     acc[a][b][m][n] = __builtin_shufflevector(z0, z1, 0, 1, 2, 3); }
;         }
;         cur = nxt; cA = nA; cB = nB; ++ui;
;         if (wr == 1) PG8_BAR;
;     template <int QVV> __device__ __forceinline__ void run(f32x4 (&acc)[2][2][4][2], const Unit& u, int wr, int wc, int fr, int fq) const {
;     ...
;             for (int m = 0; m < 4; ++m) { if (ai >= nai) continue;
;                 const float r = rs[ai][m], rn = r * (-LOG2E);
;                 f32x4 o[2];
; #pragma unroll
;                 for (int n = 0; n < 2; ++n) {
;                     const f32x4 gt = acc[ai][0][m][n] * r + sg[n], up = acc[ai][1][m][n] * r + su[n], ex = acc[ai][0][m][n] * rn + sgn[n];
;                     f32x4 den, rc;
; #pragma unroll
;                     for (int i = 0; i < 4; ++i) den[i] = __builtin_amdgcn_exp2f(ex[i]);
;                     den = den + 1.0f;
; #pragma unroll
;                     for (int i = 0; i < 4; ++i) rc[i] = __builtin_amdgcn_rcpf(den[i]);
;                     o[n] = (gt * up) * rc; }
;                 u32x4 w; w.x = pk2(o[0][0], o[0][1]); w.y = pk2(o[0][2], o[0][3]); w.z = pk2(o[1][0], o[1][1]); w.w = pk2(o[1][2], o[1][3]);
;                 *(u32x4*)(tb + lo + (unsigned)(ai * HALF + m * 16) * (DFF * 2)) = w; }
	v_pk_fma_f32 v[42:43], v[42:43], v[160:161], v[98:99] op_sel_hi:[1,0,1]
	v_rcp_f32_e32 v66, v66
	v_rcp_f32_e32 v67, v67
	v_pk_mul_f32 v[42:43], v[46:47], v[42:43]
	v_pk_mul_f32 v[44:45], v[48:49], v[44:45]
	v_pk_fma_f32 v[46:47], v[40:41], v[54:55], v[150:151] op_sel_hi:[1,0,1]
	v_pk_fma_f32 v[48:49], v[38:39], v[54:55], v[152:153] op_sel_hi:[1,0,1]
	v_exp_f32_e32 v48, v48
	v_exp_f32_e32 v46, v46
	v_exp_f32_e32 v47, v47
	v_exp_f32_e32 v49, v49
	v_pk_mul_f32 v[60:61], v[60:61], v[66:67]
	s_mov_b32 s30, 0x158000
	v_cvt_pk_bf16_f32 v51, v60, v61
	v_add_co_u32_e32 v60, vcc, s30, v146
	v_pk_add_f32 v[46:47], v[46:47], 1.0 op_sel_hi:[1,0]
	s_nop 0
	v_addc_co_u32_e32 v61, vcc, 0, v147, vcc
	v_pk_add_f32 v[48:49], v[48:49], 1.0 op_sel_hi:[1,0]
	global_store_dwordx4 v[60:61], v[50:53], off
	v_rcp_f32_e32 v48, v48
	v_rcp_f32_e32 v49, v49
	v_pk_add_f32 v[52:53], v[58:59], 1.0 op_sel_hi:[1,0]
	v_rcp_f32_e32 v46, v46
	v_rcp_f32_e32 v47, v47
	v_rcp_f32_e32 v52, v52
	v_rcp_f32_e32 v53, v53
	v_pk_fma_f32 v[40:41], v[40:41], v[160:161], v[88:89] op_sel_hi:[1,0,1]
	v_pk_fma_f32 v[38:39], v[38:39], v[160:161], v[86:87] op_sel_hi:[1,0,1]
	v_pk_fma_f32 v[36:37], v[36:37], v[160:161], v[84:85] op_sel_hi:[1,0,1]
	v_pk_fma_f32 v[34:35], v[34:35], v[160:161], v[82:83] op_sel_hi:[1,0,1]
	v_pk_mul_f32 v[36:37], v[40:41], v[36:37]
	v_pk_mul_f32 v[34:35], v[38:39], v[34:35]
	v_pk_mul_f32 v[38:39], v[36:37], v[46:47]
	v_pk_mul_f32 v[36:37], v[34:35], v[48:49]
	v_pk_mul_f32 v[42:43], v[42:43], v[52:53]
	v_cvt_pk_bf16_f32 v36, v36, v37
	v_cvt_pk_bf16_f32 v37, v38, v39
	v_mul_f32_e32 v38, 0xbfb8aa3b, v158
	v_exp_f32_e32 v57, v55
	v_cvt_pk_bf16_f32 v34, v42, v43
	v_pk_fma_f32 v[42:43], v[30:31], v[38:39], v[156:157] op_sel_hi:[1,0,1]
	v_pk_mul_f32 v[40:41], v[32:33], v[38:39] op_sel_hi:[1,0]
	v_exp_f32_e32 v42, v42
	v_exp_f32_e32 v43, v43
	v_add_f32_e32 v39, v154, v40
	v_pk_add_f32 v[50:51], v[56:57], 1.0 op_sel_hi:[1,0]
	v_exp_f32_e32 v40, v39
	v_add_f32_e32 v39, v155, v41
	v_pk_fma_f32 v[32:33], v[32:33], v[158:159], v[104:105] op_sel_hi:[1,0,1]
	v_pk_fma_f32 v[30:31], v[30:31], v[158:159], v[102:103] op_sel_hi:[1,0,1]
	v_pk_fma_f32 v[28:29], v[28:29], v[158:159], v[100:101] op_sel_hi:[1,0,1]
	v_pk_fma_f32 v[26:27], v[26:27], v[158:159], v[98:99] op_sel_hi:[1,0,1]
	v_rcp_f32_e32 v50, v50
	v_rcp_f32_e32 v51, v51
	v_pk_mul_f32 v[26:27], v[30:31], v[26:27]
	v_pk_mul_f32 v[28:29], v[32:33], v[28:29]
	v_pk_fma_f32 v[30:31], v[24:25], v[38:39], v[150:151] op_sel_hi:[1,0,1]
	v_pk_fma_f32 v[32:33], v[22:23], v[38:39], v[152:153] op_sel_hi:[1,0,1]
	v_exp_f32_e32 v32, v32
	v_exp_f32_e32 v30, v30
	v_exp_f32_e32 v31, v31
	v_exp_f32_e32 v33, v33
	v_pk_mul_f32 v[44:45], v[44:45], v[50:51]
	s_mov_b32 s30, 0x183000
	v_cvt_pk_bf16_f32 v35, v44, v45
	v_add_co_u32_e32 v44, vcc, s30, v146
	v_pk_add_f32 v[30:31], v[30:31], 1.0 op_sel_hi:[1,0]
	s_nop 0
	v_addc_co_u32_e32 v45, vcc, 0, v147, vcc
	v_pk_add_f32 v[32:33], v[32:33], 1.0 op_sel_hi:[1,0]
	v_fmamk_f32 v148, v188, 0x30000000, v231
	global_store_dwordx4 v[44:45], v[34:37], off
	v_rcp_f32_e32 v32, v32
	v_rcp_f32_e32 v33, v33
	v_pk_add_f32 v[36:37], v[42:43], 1.0 op_sel_hi:[1,0]
	v_rcp_f32_e32 v30, v30
	v_rcp_f32_e32 v31, v31
	v_rsq_f32_e32 v148, v148
	v_rcp_f32_e32 v36, v36
	v_rcp_f32_e32 v37, v37
	v_pk_fma_f32 v[24:25], v[24:25], v[158:159], v[88:89] op_sel_hi:[1,0,1]
	v_pk_fma_f32 v[22:23], v[22:23], v[158:159], v[86:87] op_sel_hi:[1,0,1]
	v_pk_fma_f32 v[20:21], v[20:21], v[158:159], v[84:85] op_sel_hi:[1,0,1]
	v_pk_fma_f32 v[18:19], v[18:19], v[158:159], v[82:83] op_sel_hi:[1,0,1]
	v_pk_mul_f32 v[20:21], v[24:25], v[20:21]
	v_pk_mul_f32 v[18:19], v[22:23], v[18:19]
	v_pk_mul_f32 v[22:23], v[20:21], v[30:31]
	v_pk_mul_f32 v[20:21], v[18:19], v[32:33]
	v_pk_mul_f32 v[26:27], v[26:27], v[36:37]
	v_cvt_pk_bf16_f32 v20, v20, v21
	v_cvt_pk_bf16_f32 v21, v22, v23
	v_mul_f32_e32 v22, 0xbfb8aa3b, v148
	v_cvt_pk_bf16_f32 v18, v26, v27
	v_pk_fma_f32 v[26:27], v[14:15], v[22:23], v[156:157] op_sel_hi:[1,0,1]
	v_exp_f32_e32 v41, v39
	v_pk_mul_f32 v[24:25], v[16:17], v[22:23] op_sel_hi:[1,0]
	v_exp_f32_e32 v26, v26
	v_exp_f32_e32 v27, v27
	v_add_f32_e32 v23, v154, v24
	v_exp_f32_e32 v24, v23
	v_add_f32_e32 v23, v155, v25
	v_pk_fma_f32 v[16:17], v[16:17], v[148:149], v[104:105] op_sel_hi:[1,0,1]
	v_pk_fma_f32 v[14:15], v[14:15], v[148:149], v[102:103] op_sel_hi:[1,0,1]
	v_pk_fma_f32 v[12:13], v[12:13], v[148:149], v[100:101] op_sel_hi:[1,0,1]
	v_pk_fma_f32 v[10:11], v[10:11], v[148:149], v[98:99] op_sel_hi:[1,0,1]
	v_pk_add_f32 v[34:35], v[40:41], 1.0 op_sel_hi:[1,0]
	v_pk_mul_f32 v[10:11], v[14:15], v[10:11]
	v_pk_mul_f32 v[12:13], v[16:17], v[12:13]
	v_pk_fma_f32 v[14:15], v[8:9], v[22:23], v[150:151] op_sel_hi:[1,0,1]
	v_pk_fma_f32 v[16:17], v[6:7], v[22:23], v[152:153] op_sel_hi:[1,0,1]
	v_rcp_f32_e32 v34, v34
	v_rcp_f32_e32 v35, v35
	v_exp_f32_e32 v16, v16
	v_exp_f32_e32 v14, v14
	v_exp_f32_e32 v15, v15
	v_exp_f32_e32 v17, v17
	v_exp_f32_e32 v25, v23
	v_pk_mul_f32 v[28:29], v[28:29], v[34:35]
	s_mov_b32 s30, 0x1ae000
	v_cvt_pk_bf16_f32 v19, v28, v29
	v_add_co_u32_e32 v28, vcc, s30, v146
	v_pk_add_f32 v[14:15], v[14:15], 1.0 op_sel_hi:[1,0]
	v_pk_add_f32 v[16:17], v[16:17], 1.0 op_sel_hi:[1,0]
	v_addc_co_u32_e32 v29, vcc, 0, v147, vcc
	v_rcp_f32_e32 v16, v16
	v_rcp_f32_e32 v17, v17
	v_rcp_f32_e32 v14, v14
	v_rcp_f32_e32 v15, v15
	global_store_dwordx4 v[28:29], v[18:21], off
	v_pk_fma_f32 v[8:9], v[8:9], v[148:149], v[88:89] op_sel_hi:[1,0,1]
	v_pk_fma_f32 v[6:7], v[6:7], v[148:149], v[86:87] op_sel_hi:[1,0,1]
	v_pk_add_f32 v[18:19], v[24:25], 1.0 op_sel_hi:[1,0]
	v_pk_add_f32 v[20:21], v[26:27], 1.0 op_sel_hi:[1,0]
	v_rcp_f32_e32 v18, v18
	v_rcp_f32_e32 v20, v20
	v_rcp_f32_e32 v21, v21
	v_rcp_f32_e32 v19, v19
	v_pk_fma_f32 v[4:5], v[4:5], v[148:149], v[84:85] op_sel_hi:[1,0,1]
	v_pk_fma_f32 v[2:3], v[2:3], v[148:149], v[82:83] op_sel_hi:[1,0,1]
	v_pk_mul_f32 v[4:5], v[8:9], v[4:5]
	v_pk_mul_f32 v[2:3], v[6:7], v[2:3]
	v_pk_mul_f32 v[6:7], v[4:5], v[14:15]
	v_pk_mul_f32 v[4:5], v[2:3], v[16:17]
	v_pk_mul_f32 v[12:13], v[12:13], v[18:19]
	v_cvt_pk_bf16_f32 v4, v4, v5
	v_cvt_pk_bf16_f32 v5, v6, v7
	v_add_co_u32_e32 v6, vcc, 0x1d9000, v146
	v_pk_mul_f32 v[10:11], v[10:11], v[20:21]
	s_nop 0
	v_addc_co_u32_e32 v7, vcc, 0, v147, vcc
	v_cvt_pk_bf16_f32 v2, v10, v11
	v_cvt_pk_bf16_f32 v3, v12, v13
	s_andn2_b64 vcc, exec, s[38:39]
	s_mov_b64 s[30:31], -1
	global_store_dwordx4 v[6:7], v[2:5], off
	s_cbranch_vccnz .LBB0_215
	s_andn2_b64 vcc, exec, s[44:45]
	v_mov_b64 v[2:3], 0
	v_mov_b64 v[4:5], 0
	s_cbranch_vccnz .LBB0_214
	s_barrier
	s_branch .LBB0_214

; __device__ __forceinline__ void row_rstd(const unsigned long long* ssq, int row0, float (&rs)[2][4]) {
;     unsigned long long q[2][4];
; #pragma unroll
;     for (int ai = 0; ai < 2; ++ai)
; #pragma unroll
;         for (int m = 0; m < 4; ++m) q[ai][m] = ssq[row0 + ai * HALF + m * 16];
;     asm volatile("" : "+v"(q[0][0]), "+v"(q[0][1]), "+v"(q[0][2]), "+v"(q[0][3]), "+v"(q[1][0]), "+v"(q[1][1]), "+v"(q[1][2]), "+v"(q[1][3]));
; #pragma unroll
;     for (int ai = 0; ai < 2; ++ai)
; #pragma unroll
;         for (int m = 0; m < 4; ++m) {
;             const float qf = __builtin_fmaf((float)(unsigned)(q[ai][m] >> 32), 4294967296.0f, (float)(unsigned)q[ai][m]);
;     template <int QVV> __device__ __forceinline__ void run(f32x4 (&acc)[2][2][4][2], const Unit& u, int wr, int wc, int fr, int fq) const {
;         constexpr int nai = (QVV == 2) ? 1 : 2; const int r0 = u.pm * BM + (QVV == 2 ? (u.seg - 1) * HALF : 0);
;         char* tb = (char*)(O + (size_t)r0 * DFF + u.pn * HALF);
;         const int v = u.pm < 4 ? 4 : ((u.pm - 4) >> 5);
;         const char* swb = (const char*)(sw + (size_t)v * SWLD + u.pn * BM);
;         unsigned lo = (unsigned)((wr * 64 + fr) * DFF + wc * 32 + 8 * fq) * 2u;
;         unsigned co = (unsigned)(wc * 32 + 8 * fq) * 4u;
;         asm volatile("" : "+v"(lo), "+v"(co));
;         float rs[2][4]; row_rstd(ssq, r0 + wr * 64 + fr, rs);
;         f32x4 sg[2], su[2], sgn[2];
; #pragma unroll
;         for (int n = 0; n < 2; ++n) { sg[n] = *(const f32x4*)(swb + co + n * 16); su[n] = *(const f32x4*)(swb + co + HALF * 4 + n * 16); sgn[n] = sg[n] * (-LOG2E); }
; #pragma unroll
;         for (int ai = 0; ai < 2; ++ai)
; #pragma unroll
;             for (int m = 0; m < 4; ++m) { if (ai >= nai) continue;
;                 const float r = rs[ai][m], rn = r * (-LOG2E);
;                 f32x4 o[2];
; #pragma unroll
;                 for (int n = 0; n < 2; ++n) {
;                     const f32x4 gt = acc[ai][0][m][n] * r + sg[n], up = acc[ai][1][m][n] * r + su[n], ex = acc[ai][0][m][n] * rn + sgn[n];
;                     f32x4 den, rc;
; #pragma unroll
;                     for (int i = 0; i < 4; ++i) den[i] = __builtin_amdgcn_exp2f(ex[i]);
;                     den = den + 1.0f;
; #pragma unroll
;                     for (int i = 0; i < 4; ++i) rc[i] = __builtin_amdgcn_rcpf(den[i]);
;                     o[n] = (gt * up) * rc; }
.LBB0_245:
	s_movk_i32 s8, 0x1580
	v_mul_lo_u32 v66, v70, s8
	s_lshl_b32 s8, s10, 8
	v_readlane_b32 s10, v253, 9
	v_or3_b32 v66, v66, v71, s19
	s_or_b32 s8, s8, s10
	v_or_b32_e32 v67, s19, v71
	v_lshlrev_b32_e32 v86, 1, v66
	v_add_u32_e32 v66, s8, v70
	v_lshlrev_b32_e32 v82, 2, v67
	v_ashrrev_i32_e32 v67, 31, v66
	v_lshl_add_u64 v[66:67], v[66:67], 3, s[34:35]
	global_load_dwordx2 v[84:85], v[66:67], off
	global_load_dwordx2 v[88:89], v[66:67], off offset:128
	global_load_dwordx2 v[90:91], v[66:67], off offset:256
	global_load_dwordx2 v[92:93], v[66:67], off offset:384
	global_load_dwordx2 v[68:69], v[66:67], off offset:1024
	global_load_dwordx2 v[70:71], v[66:67], off offset:1152
	global_load_dwordx2 v[72:73], v[66:67], off offset:1280
	s_nop 0
	global_load_dwordx2 v[66:67], v[66:67], off offset:1408
	s_mul_hi_i32 s10, s8, 0x2b00
	s_mulk_i32 s8, 0x2b00
	s_add_u32 s5, s5, s8
	s_addc_u32 s7, s7, s10
	s_lshl_b32 s10, s9, 7
	s_ashr_i32 s11, s10, 31
	s_lshl_b64 s[10:11], s[10:11], 1
	s_add_u32 s30, s5, s10
	s_addc_u32 s31, s7, s11
	s_lshl_b64 s[10:11], s[38:39], 2
	s_add_u32 s5, s2, s10
	s_addc_u32 s7, s3, s11
	s_lshl_b32 s2, s9, 8
	s_ashr_i32 s3, s2, 31
	s_lshl_b64 s[2:3], s[2:3], 2
	s_add_u32 s2, s5, s2
	s_addc_u32 s3, s7, s3
	v_mov_b32_e32 v87, v175
	s_waitcnt vmcnt(0)
	global_load_dwordx4 v[78:81], v82, s[2:3]
	global_load_dwordx4 v[70:73], v82, s[2:3] offset:16
	global_load_dwordx4 v[74:77], v82, s[2:3] offset:512
	global_load_dwordx4 v[66:69], v82, s[2:3] offset:528
	s_flbit_i32_b32 s2, 0
	s_min_u32 s2, s2, 32
	v_mov_b32_e32 v174, v89
	v_lshl_add_u64 v[82:83], s[30:31], 0, v[86:87]
	v_cvt_f32_u32_e32 v87, v88
	v_lshlrev_b64 v[88:89], s2, v[174:175]
	v_mov_b32_e32 v174, v91
	v_cvt_f32_u32_e32 v95, v90
	v_cvt_f32_u32_e32 v96, v84
	v_min_u32_e32 v84, 1, v88
	v_lshlrev_b64 v[90:91], s2, v[174:175]
	v_mov_b32_e32 v174, v93
	v_or_b32_e32 v84, v89, v84
	v_min_u32_e32 v90, 1, v90
	v_lshlrev_b64 v[88:89], s2, v[174:175]
	v_mov_b32_e32 v174, v85
	v_cvt_f32_u32_e32 v93, v84
	v_or_b32_e32 v90, v91, v90
	v_min_u32_e32 v88, 1, v88
	v_lshlrev_b64 v[84:85], s2, v[174:175]
	v_cvt_f32_u32_e32 v90, v90
	v_or_b32_e32 v88, v89, v88
	v_min_u32_e32 v84, 1, v84
	v_cvt_f32_u32_e32 v88, v88
	v_or_b32_e32 v84, v85, v84
	s_sub_i32 s3, 32, s2
	v_cvt_f32_u32_e32 v92, v92
	v_cvt_f32_u32_e32 v84, v84
	v_ldexp_f32 v85, v93, s3
	v_fmac_f32_e32 v87, 0x4f800000, v85
	v_ldexp_f32 v85, v90, s3
	v_fmac_f32_e32 v95, 0x4f800000, v85
	v_ldexp_f32 v85, v88, s3
	v_fmac_f32_e32 v92, 0x4f800000, v85
	v_ldexp_f32 v84, v84, s3
	v_fmamk_f32 v87, v87, 0x30000000, v231
	v_fmamk_f32 v85, v92, 0x30000000, v231
	v_fmac_f32_e32 v96, 0x4f800000, v84
	v_rsq_f32_e32 v94, v87
	v_rsq_f32_e32 v84, v85
	v_fmamk_f32 v85, v96, 0x30000000, v231
	v_rsq_f32_e32 v96, v85
	v_mul_f32_e32 v90, 0xbfb8aa3b, v94
	v_pk_mul_f32 v[98:99], v[56:57], v[90:91] op_sel_hi:[1,0]
	v_pk_mul_f32 v[100:101], v[54:55], v[90:91] op_sel_hi:[1,0]
	v_pk_mul_f32 v[102:103], v[40:41], v[90:91] op_sel_hi:[1,0]
	v_pk_mul_f32 v[104:105], v[38:39], v[90:91] op_sel_hi:[1,0]
	v_mul_f32_e32 v90, 0xbfb8aa3b, v96
	s_mov_b32 s2, 0xbfb8aa3b
	v_fmamk_f32 v87, v95, 0x30000000, v231
	v_pk_mul_f32 v[106:107], v[64:65], v[90:91] op_sel_hi:[1,0]
	v_pk_mul_f32 v[108:109], v[62:63], v[90:91] op_sel_hi:[1,0]
	v_pk_mul_f32 v[110:111], v[60:61], v[90:91] op_sel_hi:[1,0]
	v_pk_mul_f32 v[112:113], v[58:59], v[90:91] op_sel_hi:[1,0]
	v_rsq_f32_e32 v88, v87
	s_waitcnt vmcnt(3)
	v_pk_mul_f32 v[114:115], v[80:81], s[2:3] op_sel_hi:[1,0]
	v_pk_mul_f32 v[116:117], v[78:79], s[2:3] op_sel_hi:[1,0]
	s_waitcnt vmcnt(2)
	v_pk_mul_f32 v[90:91], v[72:73], s[2:3] op_sel_hi:[1,0]
	v_pk_mul_f32 v[92:93], v[70:71], s[2:3] op_sel_hi:[1,0]
	v_pk_fma_f32 v[64:65], v[64:65], v[96:97], v[80:81] op_sel_hi:[1,0,1]
	v_pk_fma_f32 v[62:63], v[62:63], v[96:97], v[78:79] op_sel_hi:[1,0,1]
	s_waitcnt vmcnt(1)
	v_pk_fma_f32 v[52:53], v[52:53], v[96:97], v[76:77] op_sel_hi:[1,0,1]
	v_pk_fma_f32 v[50:51], v[50:51], v[96:97], v[74:75] op_sel_hi:[1,0,1]
	v_pk_fma_f32 v[60:61], v[60:61], v[96:97], v[72:73] op_sel_hi:[1,0,1]
	v_pk_fma_f32 v[58:59], v[58:59], v[96:97], v[70:71] op_sel_hi:[1,0,1]
	s_waitcnt vmcnt(0)
	v_pk_fma_f32 v[48:49], v[48:49], v[96:97], v[68:69] op_sel_hi:[1,0,1]
	v_pk_fma_f32 v[46:47], v[46:47], v[96:97], v[66:67] op_sel_hi:[1,0,1]
	v_pk_fma_f32 v[56:57], v[56:57], v[94:95], v[80:81] op_sel_hi:[1,0,1]
	v_pk_fma_f32 v[54:55], v[54:55], v[94:95], v[78:79] op_sel_hi:[1,0,1]
	v_pk_fma_f32 v[44:45], v[44:45], v[94:95], v[76:77] op_sel_hi:[1,0,1]
	v_pk_fma_f32 v[42:43], v[42:43], v[94:95], v[74:75] op_sel_hi:[1,0,1]
	v_add_f32_e32 v85, v116, v108
	v_add_f32_e32 v87, v117, v109
	v_add_f32_e32 v89, v114, v106
	v_add_f32_e32 v95, v115, v107
	v_pk_mul_f32 v[50:51], v[62:63], v[50:51]
	v_pk_mul_f32 v[52:53], v[64:65], v[52:53]
	v_add_f32_e32 v62, v92, v112
	v_add_f32_e32 v63, v93, v113
	v_add_f32_e32 v64, v90, v110
	v_add_f32_e32 v65, v91, v111
	v_pk_mul_f32 v[46:47], v[58:59], v[46:47]
	v_pk_mul_f32 v[48:49], v[60:61], v[48:49]
	v_add_f32_e32 v96, v116, v100
	v_add_f32_e32 v97, v117, v101
	v_add_f32_e32 v98, v114, v98
	v_add_f32_e32 v99, v115, v99
	v_pk_mul_f32 v[42:43], v[54:55], v[42:43]
	v_pk_mul_f32 v[44:45], v[56:57], v[44:45]
	v_exp_f32_e32 v54, v85
	v_exp_f32_e32 v55, v87
	v_exp_f32_e32 v56, v89
	v_exp_f32_e32 v57, v95
	v_exp_f32_e32 v58, v62
	v_exp_f32_e32 v59, v63
	v_exp_f32_e32 v60, v64
	v_exp_f32_e32 v61, v65
	v_exp_f32_e32 v62, v96
	v_exp_f32_e32 v63, v97
	v_exp_f32_e32 v64, v98
	v_exp_f32_e32 v65, v99
	v_pk_add_f32 v[56:57], v[56:57], 1.0 op_sel_hi:[1,0]
	v_pk_add_f32 v[54:55], v[54:55], 1.0 op_sel_hi:[1,0]
	v_pk_add_f32 v[60:61], v[60:61], 1.0 op_sel_hi:[1,0]
; #define PG8_WAIT_V(n) asm volatile("s_waitcnt vmcnt(" #n ")" ::: "memory")
; #define PG8_BAR __builtin_amdgcn_s_barrier()
;     ...
;     PG8_WAIT_V(0);
;     PG8_BAR;
;     template <int QVV> __device__ __forceinline__ void run(f32x4 (&acc)[2][2][4][2], const Unit& u, int wr, int wc, int fr, int fq) const {
;     ...
;             for (int m = 0; m < 4; ++m) { if (ai >= nai) continue;
;                 const float r = rs[ai][m], rn = r * (-LOG2E);
;                 f32x4 o[2];
; #pragma unroll
;                 for (int n = 0; n < 2; ++n) {
;                     const f32x4 gt = acc[ai][0][m][n] * r + sg[n], up = acc[ai][1][m][n] * r + su[n], ex = acc[ai][0][m][n] * rn + sgn[n];
;                     f32x4 den, rc;
; #pragma unroll
;                     for (int i = 0; i < 4; ++i) den[i] = __builtin_amdgcn_exp2f(ex[i]);
;                     den = den + 1.0f;
; #pragma unroll
;                     for (int i = 0; i < 4; ++i) rc[i] = __builtin_amdgcn_rcpf(den[i]);
;                     o[n] = (gt * up) * rc; }
;                 u32x4 w; w.x = pk2(o[0][0], o[0][1]); w.y = pk2(o[0][2], o[0][3]); w.z = pk2(o[1][0], o[1][1]); w.w = pk2(o[1][2], o[1][3]);
;                 *(u32x4*)(tb + lo + (unsigned)(ai * HALF + m * 16) * (DFF * 2)) = w; }
	v_pk_add_f32 v[58:59], v[58:59], 1.0 op_sel_hi:[1,0]
	v_pk_add_f32 v[64:65], v[64:65], 1.0 op_sel_hi:[1,0]
	v_pk_add_f32 v[62:63], v[62:63], 1.0 op_sel_hi:[1,0]
	v_rcp_f32_e32 v54, v54
	v_rcp_f32_e32 v55, v55
	v_rcp_f32_e32 v56, v56
	v_rcp_f32_e32 v57, v57
	v_rcp_f32_e32 v58, v58
	v_rcp_f32_e32 v59, v59
	v_rcp_f32_e32 v60, v60
	v_rcp_f32_e32 v61, v61
	v_add_f32_e32 v100, v92, v104
	v_add_f32_e32 v101, v93, v105
	v_add_f32_e32 v102, v90, v102
	v_add_f32_e32 v103, v91, v103
	v_rcp_f32_e32 v62, v62
	v_rcp_f32_e32 v63, v63
	v_rcp_f32_e32 v64, v64
	v_rcp_f32_e32 v65, v65
	v_exp_f32_e32 v96, v100
	v_exp_f32_e32 v97, v101
	v_exp_f32_e32 v98, v102
	v_exp_f32_e32 v99, v103
	v_pk_mul_f32 v[52:53], v[52:53], v[56:57]
	v_pk_mul_f32 v[50:51], v[50:51], v[54:55]
	v_pk_mul_f32 v[48:49], v[48:49], v[60:61]
	v_pk_mul_f32 v[46:47], v[46:47], v[58:59]
	v_pk_mul_f32 v[54:55], v[44:45], v[64:65]
	v_pk_mul_f32 v[56:57], v[42:43], v[62:63]
	v_cvt_pk_bf16_f32 v42, v50, v51
	v_cvt_pk_bf16_f32 v43, v52, v53
	v_cvt_pk_bf16_f32 v44, v46, v47
	v_cvt_pk_bf16_f32 v45, v48, v49
	v_pk_add_f32 v[98:99], v[98:99], 1.0 op_sel_hi:[1,0]
	global_store_dwordx4 v86, v[42:45], s[30:31]
	v_pk_fma_f32 v[40:41], v[40:41], v[94:95], v[72:73] op_sel_hi:[1,0,1]
	v_pk_fma_f32 v[38:39], v[38:39], v[94:95], v[70:71] op_sel_hi:[1,0,1]
	v_pk_add_f32 v[42:43], v[96:97], 1.0 op_sel_hi:[1,0]
	v_rcp_f32_e32 v44, v98
	v_rcp_f32_e32 v42, v42
	v_rcp_f32_e32 v43, v43
	v_rcp_f32_e32 v45, v99
	v_pk_fma_f32 v[36:37], v[36:37], v[94:95], v[68:69] op_sel_hi:[1,0,1]
	v_pk_fma_f32 v[34:35], v[34:35], v[94:95], v[66:67] op_sel_hi:[1,0,1]
	v_pk_mul_f32 v[36:37], v[40:41], v[36:37]
	v_pk_mul_f32 v[34:35], v[38:39], v[34:35]
	v_pk_mul_f32 v[38:39], v[36:37], v[44:45]
	v_pk_mul_f32 v[36:37], v[34:35], v[42:43]
	v_pk_fma_f32 v[28:29], v[28:29], v[88:89], v[76:77] op_sel_hi:[1,0,1]
	v_cvt_pk_bf16_f32 v36, v36, v37
	v_cvt_pk_bf16_f32 v37, v38, v39
	v_mul_f32_e32 v38, 0xbfb8aa3b, v88
	v_pk_fma_f32 v[42:43], v[30:31], v[38:39], v[116:117] op_sel_hi:[1,0,1]
	v_pk_mul_f32 v[40:41], v[32:33], v[38:39] op_sel_hi:[1,0]
	v_exp_f32_e32 v42, v42
	v_exp_f32_e32 v43, v43
	v_add_f32_e32 v39, v114, v40
	v_exp_f32_e32 v40, v39
	v_add_f32_e32 v39, v115, v41
	v_pk_fma_f32 v[32:33], v[32:33], v[88:89], v[80:81] op_sel_hi:[1,0,1]
	v_pk_fma_f32 v[30:31], v[30:31], v[88:89], v[78:79] op_sel_hi:[1,0,1]
	v_pk_fma_f32 v[26:27], v[26:27], v[88:89], v[74:75] op_sel_hi:[1,0,1]
	v_pk_mul_f32 v[28:29], v[32:33], v[28:29]
	v_pk_mul_f32 v[26:27], v[30:31], v[26:27]
	v_pk_fma_f32 v[30:31], v[24:25], v[38:39], v[90:91] op_sel_hi:[1,0,1]
	v_pk_fma_f32 v[32:33], v[22:23], v[38:39], v[92:93] op_sel_hi:[1,0,1]
	v_exp_f32_e32 v32, v32
	v_exp_f32_e32 v30, v30
	v_exp_f32_e32 v31, v31
	v_exp_f32_e32 v33, v33
	s_mov_b32 s2, 0x2b000
	v_add_co_u32_e32 v44, vcc, s2, v82
	v_cvt_pk_bf16_f32 v34, v56, v57
	v_cvt_pk_bf16_f32 v35, v54, v55
	v_addc_co_u32_e32 v45, vcc, 0, v83, vcc
	v_pk_add_f32 v[30:31], v[30:31], 1.0 op_sel_hi:[1,0]
	v_pk_add_f32 v[32:33], v[32:33], 1.0 op_sel_hi:[1,0]
	global_store_dwordx4 v[44:45], v[34:37], off
	v_rcp_f32_e32 v32, v32
	v_rcp_f32_e32 v33, v33
	v_pk_add_f32 v[36:37], v[42:43], 1.0 op_sel_hi:[1,0]
	v_rcp_f32_e32 v30, v30
	v_rcp_f32_e32 v31, v31
	v_rcp_f32_e32 v36, v36
	v_rcp_f32_e32 v37, v37
	v_pk_fma_f32 v[24:25], v[24:25], v[88:89], v[72:73] op_sel_hi:[1,0,1]
	v_pk_fma_f32 v[22:23], v[22:23], v[88:89], v[70:71] op_sel_hi:[1,0,1]
	v_pk_fma_f32 v[20:21], v[20:21], v[88:89], v[68:69] op_sel_hi:[1,0,1]
	v_pk_fma_f32 v[18:19], v[18:19], v[88:89], v[66:67] op_sel_hi:[1,0,1]
	v_pk_mul_f32 v[20:21], v[24:25], v[20:21]
	v_pk_mul_f32 v[18:19], v[22:23], v[18:19]
	v_pk_mul_f32 v[22:23], v[20:21], v[30:31]
	v_pk_mul_f32 v[20:21], v[18:19], v[32:33]
	v_pk_mul_f32 v[26:27], v[26:27], v[36:37]
	v_cvt_pk_bf16_f32 v20, v20, v21
	v_cvt_pk_bf16_f32 v21, v22, v23
	v_mul_f32_e32 v22, 0xbfb8aa3b, v84
	v_exp_f32_e32 v41, v39
	v_cvt_pk_bf16_f32 v18, v26, v27
	v_pk_fma_f32 v[26:27], v[14:15], v[22:23], v[116:117] op_sel_hi:[1,0,1]
	v_pk_mul_f32 v[24:25], v[16:17], v[22:23] op_sel_hi:[1,0]
	v_exp_f32_e32 v26, v26
	v_exp_f32_e32 v27, v27
	v_add_f32_e32 v23, v114, v24
	v_pk_add_f32 v[34:35], v[40:41], 1.0 op_sel_hi:[1,0]
	v_exp_f32_e32 v24, v23
	v_add_f32_e32 v23, v115, v25
	v_pk_fma_f32 v[16:17], v[16:17], v[84:85], v[80:81] op_sel_hi:[1,0,1]
	v_pk_fma_f32 v[14:15], v[14:15], v[84:85], v[78:79] op_sel_hi:[1,0,1]
	v_pk_fma_f32 v[12:13], v[12:13], v[84:85], v[76:77] op_sel_hi:[1,0,1]
	v_pk_fma_f32 v[10:11], v[10:11], v[84:85], v[74:75] op_sel_hi:[1,0,1]
	v_rcp_f32_e32 v34, v34
	v_rcp_f32_e32 v35, v35
	v_pk_mul_f32 v[10:11], v[14:15], v[10:11]
	v_pk_mul_f32 v[12:13], v[16:17], v[12:13]
	v_pk_fma_f32 v[14:15], v[8:9], v[22:23], v[90:91] op_sel_hi:[1,0,1]
	v_pk_fma_f32 v[16:17], v[6:7], v[22:23], v[92:93] op_sel_hi:[1,0,1]
	v_exp_f32_e32 v16, v16
	v_exp_f32_e32 v14, v14
	v_exp_f32_e32 v15, v15
	v_exp_f32_e32 v17, v17
	v_exp_f32_e32 v25, v23
	v_pk_mul_f32 v[28:29], v[28:29], v[34:35]
	s_mov_b32 s2, 0x56000
	v_cvt_pk_bf16_f32 v19, v28, v29
	v_add_co_u32_e32 v28, vcc, s2, v82
	v_pk_add_f32 v[14:15], v[14:15], 1.0 op_sel_hi:[1,0]
	s_nop 0
	v_addc_co_u32_e32 v29, vcc, 0, v83, vcc
	v_pk_add_f32 v[16:17], v[16:17], 1.0 op_sel_hi:[1,0]
	global_store_dwordx4 v[28:29], v[18:21], off
	v_rcp_f32_e32 v16, v16
	v_rcp_f32_e32 v17, v17
	v_pk_add_f32 v[18:19], v[24:25], 1.0 op_sel_hi:[1,0]
	v_pk_add_f32 v[20:21], v[26:27], 1.0 op_sel_hi:[1,0]
	v_rcp_f32_e32 v14, v14
	v_rcp_f32_e32 v15, v15
	v_rcp_f32_e32 v20, v20
	v_rcp_f32_e32 v21, v21
	v_rcp_f32_e32 v18, v18
	v_rcp_f32_e32 v19, v19
	v_pk_fma_f32 v[8:9], v[8:9], v[84:85], v[72:73] op_sel_hi:[1,0,1]
	v_pk_fma_f32 v[6:7], v[6:7], v[84:85], v[70:71] op_sel_hi:[1,0,1]
	v_pk_fma_f32 v[4:5], v[4:5], v[84:85], v[68:69] op_sel_hi:[1,0,1]
	v_pk_fma_f32 v[2:3], v[2:3], v[84:85], v[66:67] op_sel_hi:[1,0,1]
	v_pk_mul_f32 v[4:5], v[8:9], v[4:5]
	v_pk_mul_f32 v[2:3], v[6:7], v[2:3]
	v_pk_mul_f32 v[6:7], v[4:5], v[14:15]
	v_pk_mul_f32 v[4:5], v[2:3], v[16:17]
	v_pk_mul_f32 v[12:13], v[12:13], v[18:19]
	v_pk_mul_f32 v[10:11], v[10:11], v[20:21]
	v_cvt_pk_bf16_f32 v4, v4, v5
	v_cvt_pk_bf16_f32 v5, v6, v7
	v_add_co_u32_e32 v6, vcc, 0x81000, v82
	v_cvt_pk_bf16_f32 v2, v10, v11
	v_cvt_pk_bf16_f32 v3, v12, v13
	v_addc_co_u32_e32 v7, vcc, 0, v83, vcc
	global_store_dwordx4 v[6:7], v[2:5], off
	s_waitcnt vmcnt(0)
	s_barrier

; __device__ __forceinline__ void row_rstd(const unsigned long long* ssq, int row0, float (&rs)[2][4]) {
;     unsigned long long q[2][4];
; #pragma unroll
;     for (int ai = 0; ai < 2; ++ai)
; #pragma unroll
;         for (int m = 0; m < 4; ++m) q[ai][m] = ssq[row0 + ai * HALF + m * 16];
;     asm volatile("" : "+v"(q[0][0]), "+v"(q[0][1]), "+v"(q[0][2]), "+v"(q[0][3]), "+v"(q[1][0]), "+v"(q[1][1]), "+v"(q[1][2]), "+v"(q[1][3]));
; #pragma unroll
;     for (int ai = 0; ai < 2; ++ai)
; #pragma unroll
;         for (int m = 0; m < 4; ++m) {
;             const float qf = __builtin_fmaf((float)(unsigned)(q[ai][m] >> 32), 4294967296.0f, (float)(unsigned)q[ai][m]);
;             rs[ai][m] = __builtin_amdgcn_rsqf(__builtin_fmaf(qf, 1.0f / (SSQ_SCALE * DM), EPS)); }
; }
;     template <int QVV> __device__ __forceinline__ void run(f32x4 (&acc)[2][2][4][2], const Unit& u, int wr, int wc, int fr, int fq) const {
;         constexpr int nai = (QVV == 2) ? 1 : 2; const int r0 = u.pm * BM + (QVV == 2 ? (u.seg - 1) * HALF : 0);
;         char* tb = (char*)(O + (size_t)r0 * DFF + u.pn * HALF);
;         const int v = u.pm < 4 ? 4 : ((u.pm - 4) >> 5);
;         const char* swb = (const char*)(sw + (size_t)v * SWLD + u.pn * BM);
;         unsigned lo = (unsigned)((wr * 64 + fr) * DFF + wc * 32 + 8 * fq) * 2u;
;         unsigned co = (unsigned)(wc * 32 + 8 * fq) * 4u;
;         asm volatile("" : "+v"(lo), "+v"(co));
;         float rs[2][4]; row_rstd(ssq, r0 + wr * 64 + fr, rs);
;         f32x4 sg[2], su[2], sgn[2];
; #pragma unroll
;         for (int n = 0; n < 2; ++n) { sg[n] = *(const f32x4*)(swb + co + n * 16); su[n] = *(const f32x4*)(swb + co + HALF * 4 + n * 16); sgn[n] = sg[n] * (-LOG2E); }
.LBB0_1656:
	s_lshl_b32 s30, s60, 8
	v_add_u32_e32 v82, s30, v169
	v_ashrrev_i32_e32 v83, 31, v82
	v_mov_b32_e32 v98, v171
	v_mov_b32_e32 v166, v170
	v_lshl_add_u64 v[82:83], v[82:83], 3, s[34:35]
	global_load_dwordx2 v[150:151], v[82:83], off
	global_load_dwordx2 v[152:153], v[82:83], off offset:128
	global_load_dwordx2 v[154:155], v[82:83], off offset:256
	global_load_dwordx2 v[156:157], v[82:83], off offset:384
	global_load_dwordx2 v[178:179], v[82:83], off offset:1024
	global_load_dwordx2 v[180:181], v[82:83], off offset:1152
	global_load_dwordx2 v[182:183], v[82:83], off offset:1280
	global_load_dwordx2 v[184:185], v[82:83], off offset:1408
	s_mul_i32 s31, s60, 0x2b0000
	s_mul_hi_i32 s30, s30, 0x2b00
	s_add_u32 s60, s2, s31
	s_addc_u32 s61, s3, s30
	s_lshl_b32 s30, s59, 7
	s_ashr_i32 s31, s30, 31
	s_lshl_b64 s[30:31], s[30:31], 1
	s_add_u32 s30, s60, s30
	s_addc_u32 s31, s61, s31
	s_lshl_b64 s[42:43], s[42:43], 2
	s_add_u32 s60, s5, s42
	s_addc_u32 s61, s7, s43
	s_lshl_b32 s42, s59, 8
	s_ashr_i32 s43, s42, 31
	s_lshl_b64 s[42:43], s[42:43], 2
	s_add_u32 s42, s60, s42
	s_addc_u32 s43, s61, s43
	s_flbit_i32_b32 s59, 0
	s_min_u32 s59, s59, 32
	s_sub_i32 s60, 32, s59
	v_mov_b32_e32 v167, v175
	v_lshl_add_u64 v[146:147], s[30:31], 0, v[166:167]
	s_waitcnt vmcnt(0)
	global_load_dwordx4 v[86:89], v98, s[42:43] offset:16
	global_load_dwordx4 v[102:105], v98, s[42:43]
	global_load_dwordx4 v[82:85], v98, s[42:43] offset:528
	s_nop 0
	global_load_dwordx4 v[98:101], v98, s[42:43] offset:512
	v_mov_b32_e32 v174, v151
	v_cvt_f32_u32_e32 v148, v150
	v_lshlrev_b64 v[150:151], s59, v[174:175]
	v_mov_b32_e32 v174, v153
	v_cvt_f32_u32_e32 v158, v152
	v_min_u32_e32 v150, 1, v150
	v_lshlrev_b64 v[152:153], s59, v[174:175]
	v_mov_b32_e32 v174, v155
	v_or_b32_e32 v155, v151, v150
	v_min_u32_e32 v152, 1, v152
	v_lshlrev_b64 v[150:151], s59, v[174:175]
	v_mov_b32_e32 v174, v157
	v_cvt_f32_u32_e32 v155, v155
	v_or_b32_e32 v157, v153, v152
	v_min_u32_e32 v150, 1, v150
	v_lshlrev_b64 v[152:153], s59, v[174:175]
	v_mov_b32_e32 v174, v179
	v_cvt_f32_u32_e32 v157, v157
	v_or_b32_e32 v162, v151, v150
	v_min_u32_e32 v152, 1, v152
	v_lshlrev_b64 v[150:151], s59, v[174:175]
	v_mov_b32_e32 v174, v181
	v_cvt_f32_u32_e32 v162, v162
	v_or_b32_e32 v164, v153, v152
	v_min_u32_e32 v150, 1, v150
	v_lshlrev_b64 v[152:153], s59, v[174:175]
	v_mov_b32_e32 v174, v183
	v_cvt_f32_u32_e32 v154, v154
	v_cvt_f32_u32_e32 v164, v164
	v_or_b32_e32 v168, v151, v150
	v_lshlrev_b64 v[150:151], s59, v[174:175]
	v_cvt_f32_u32_e32 v156, v156
	v_min_u32_e32 v152, 1, v152
	v_mov_b32_e32 v174, v185
	v_ldexp_f32 v155, v155, s60
	v_cvt_f32_u32_e32 v168, v168
	v_min_u32_e32 v150, 1, v150
	v_cvt_f32_u32_e32 v160, v178
	v_or_b32_e32 v178, v153, v152
	v_lshlrev_b64 v[152:153], s59, v[174:175]
	v_fmac_f32_e32 v148, 0x4f800000, v155
	v_ldexp_f32 v155, v157, s60
	v_or_b32_e32 v150, v151, v150
	v_cvt_f32_u32_e32 v157, v178
	v_min_u32_e32 v151, 1, v152
	v_fmamk_f32 v148, v148, 0x30000000, v231
	v_fmac_f32_e32 v158, 0x4f800000, v155
	v_ldexp_f32 v152, v162, s60
	v_cvt_f32_u32_e32 v150, v150
	v_cvt_f32_u32_e32 v167, v180
	v_cvt_f32_u32_e32 v177, v182
	v_or_b32_e32 v151, v153, v151
	v_rsq_f32_e32 v174, v148
	v_fmamk_f32 v148, v158, 0x30000000, v231
	v_fmac_f32_e32 v154, 0x4f800000, v152
	v_ldexp_f32 v152, v164, s60
	v_cvt_f32_u32_e32 v151, v151
	v_rsq_f32_e32 v178, v148
	v_fmamk_f32 v148, v154, 0x30000000, v231
	v_fmac_f32_e32 v156, 0x4f800000, v152
	v_ldexp_f32 v152, v168, s60
	v_cvt_f32_u32_e32 v188, v184
	v_rsq_f32_e32 v168, v148
	v_fmamk_f32 v148, v156, 0x30000000, v231
	v_fmac_f32_e32 v160, 0x4f800000, v152
	v_ldexp_f32 v152, v157, s60
	v_rsq_f32_e32 v164, v148
	v_fmamk_f32 v148, v160, 0x30000000, v231
	v_ldexp_f32 v150, v150, s60
	v_fmac_f32_e32 v167, 0x4f800000, v152
	v_rsq_f32_e32 v162, v148
	v_fmac_f32_e32 v177, 0x4f800000, v150
	v_mul_f32_e32 v148, 0xbfb8aa3b, v174
	s_mov_b32 s42, 0xbfb8aa3b
	v_fmamk_f32 v152, v167, 0x30000000, v231
	v_ldexp_f32 v150, v151, s60
	v_fmamk_f32 v151, v177, 0x30000000, v231
	v_pk_mul_f32 v[182:183], v[142:143], v[148:149] op_sel_hi:[1,0]
	s_waitcnt vmcnt(2)
	v_pk_mul_f32 v[156:157], v[102:103], s[42:43] op_sel_hi:[1,0]
	v_rsq_f32_e32 v160, v152
	v_fmac_f32_e32 v188, 0x4f800000, v150
	v_pk_mul_f32 v[180:181], v[144:145], v[148:149] op_sel_hi:[1,0]
	v_pk_mul_f32 v[184:185], v[136:137], v[148:149] op_sel_hi:[1,0]
	v_pk_mul_f32 v[186:187], v[134:135], v[148:149] op_sel_hi:[1,0]
	v_rsq_f32_e32 v158, v151
	v_pk_mul_f32 v[154:155], v[104:105], s[42:43] op_sel_hi:[1,0]
	v_pk_mul_f32 v[150:151], v[88:89], s[42:43] op_sel_hi:[1,0]
	v_pk_mul_f32 v[152:153], v[86:87], s[42:43] op_sel_hi:[1,0]
	v_pk_fma_f32 v[144:145], v[144:145], v[174:175], v[104:105] op_sel_hi:[1,0,1]
	v_pk_fma_f32 v[142:143], v[142:143], v[174:175], v[102:103] op_sel_hi:[1,0,1]
	s_waitcnt vmcnt(0)
;     template <int QVV> __device__ __forceinline__ void run(f32x4 (&acc)[2][2][4][2], const Unit& u, int wr, int wc, int fr, int fq) const {
;     ...
;             for (int m = 0; m < 4; ++m) { if (ai >= nai) continue;
;                 const float r = rs[ai][m], rn = r * (-LOG2E);
;                 f32x4 o[2];
; #pragma unroll
;                 for (int n = 0; n < 2; ++n) {
;                     const f32x4 gt = acc[ai][0][m][n] * r + sg[n], up = acc[ai][1][m][n] * r + su[n], ex = acc[ai][0][m][n] * rn + sgn[n];
;                     f32x4 den, rc;
; #pragma unroll
;                     for (int i = 0; i < 4; ++i) den[i] = __builtin_amdgcn_exp2f(ex[i]);
;                     den = den + 1.0f;
; #pragma unroll
;                     for (int i = 0; i < 4; ++i) rc[i] = __builtin_amdgcn_rcpf(den[i]);
;                     o[n] = (gt * up) * rc; }
;                 u32x4 w; w.x = pk2(o[0][0], o[0][1]); w.y = pk2(o[0][2], o[0][3]); w.z = pk2(o[1][0], o[1][1]); w.w = pk2(o[1][2], o[1][3]);
;                 *(u32x4*)(tb + lo + (unsigned)(ai * HALF + m * 16) * (DFF * 2)) = w; }
	v_pk_fma_f32 v[140:141], v[140:141], v[174:175], v[100:101] op_sel_hi:[1,0,1]
	v_pk_fma_f32 v[138:139], v[138:139], v[174:175], v[98:99] op_sel_hi:[1,0,1]
	v_pk_fma_f32 v[136:137], v[136:137], v[174:175], v[88:89] op_sel_hi:[1,0,1]
	v_pk_fma_f32 v[134:135], v[134:135], v[174:175], v[86:87] op_sel_hi:[1,0,1]
	v_pk_fma_f32 v[132:133], v[132:133], v[174:175], v[84:85] op_sel_hi:[1,0,1]
	v_pk_fma_f32 v[130:131], v[130:131], v[174:175], v[82:83] op_sel_hi:[1,0,1]
	v_add_f32_e32 v167, v156, v182
	v_add_f32_e32 v174, v157, v183
	v_add_f32_e32 v177, v154, v180
	v_add_f32_e32 v179, v155, v181
	v_pk_mul_f32 v[138:139], v[142:143], v[138:139]
	v_pk_mul_f32 v[140:141], v[144:145], v[140:141]
	v_add_f32_e32 v142, v152, v186
	v_add_f32_e32 v143, v153, v187
	v_add_f32_e32 v144, v150, v184
	v_add_f32_e32 v145, v151, v185
	v_pk_mul_f32 v[130:131], v[134:135], v[130:131]
	v_exp_f32_e32 v134, v167
	v_exp_f32_e32 v135, v174
	v_pk_mul_f32 v[132:133], v[136:137], v[132:133]
	v_exp_f32_e32 v136, v177
	v_exp_f32_e32 v137, v179
	v_exp_f32_e32 v142, v142
	v_exp_f32_e32 v144, v144
	v_exp_f32_e32 v145, v145
	v_exp_f32_e32 v143, v143
	v_pk_add_f32 v[134:135], v[134:135], 1.0 op_sel_hi:[1,0]
	v_pk_add_f32 v[136:137], v[136:137], 1.0 op_sel_hi:[1,0]
	v_pk_add_f32 v[144:145], v[144:145], 1.0 op_sel_hi:[1,0]
	v_pk_add_f32 v[142:143], v[142:143], 1.0 op_sel_hi:[1,0]
	v_rcp_f32_e32 v134, v134
	v_rcp_f32_e32 v135, v135
	v_rcp_f32_e32 v136, v136
	v_rcp_f32_e32 v137, v137
	v_rcp_f32_e32 v142, v142
	v_rcp_f32_e32 v144, v144
	v_rcp_f32_e32 v145, v145
	v_rcp_f32_e32 v143, v143
	v_pk_mul_f32 v[134:135], v[138:139], v[134:135]
	v_pk_mul_f32 v[136:137], v[140:141], v[136:137]
	v_pk_mul_f32 v[138:139], v[132:133], v[144:145]
	v_pk_mul_f32 v[132:133], v[130:131], v[142:143]
	v_cvt_pk_bf16_f32 v130, v134, v135
	v_mul_f32_e32 v134, 0xbfb8aa3b, v178
	v_cvt_pk_bf16_f32 v131, v136, v137
	v_pk_mul_f32 v[136:137], v[128:129], v[134:135] op_sel_hi:[1,0]
	v_pk_fma_f32 v[140:141], v[126:127], v[134:135], v[156:157] op_sel_hi:[1,0,1]
	v_add_f32_e32 v135, v154, v136
	v_exp_f32_e32 v136, v135
	v_add_f32_e32 v135, v155, v137
	v_pk_fma_f32 v[128:129], v[128:129], v[178:179], v[104:105] op_sel_hi:[1,0,1]
	v_pk_fma_f32 v[126:127], v[126:127], v[178:179], v[102:103] op_sel_hi:[1,0,1]
	v_pk_fma_f32 v[124:125], v[124:125], v[178:179], v[100:101] op_sel_hi:[1,0,1]
	v_pk_fma_f32 v[122:123], v[122:123], v[178:179], v[98:99] op_sel_hi:[1,0,1]
	v_pk_mul_f32 v[124:125], v[128:129], v[124:125]
	v_pk_mul_f32 v[122:123], v[126:127], v[122:123]
	v_pk_fma_f32 v[126:127], v[120:121], v[134:135], v[150:151] op_sel_hi:[1,0,1]
	v_pk_fma_f32 v[128:129], v[118:119], v[134:135], v[152:153] op_sel_hi:[1,0,1]
	v_cvt_pk_bf16_f32 v132, v132, v133
	v_exp_f32_e32 v140, v140
	v_exp_f32_e32 v128, v128
	v_exp_f32_e32 v126, v126
	v_exp_f32_e32 v127, v127
	v_exp_f32_e32 v129, v129
	v_exp_f32_e32 v141, v141
	v_cvt_pk_bf16_f32 v133, v138, v139
	v_pk_add_f32 v[126:127], v[126:127], 1.0 op_sel_hi:[1,0]
	v_pk_add_f32 v[128:129], v[128:129], 1.0 op_sel_hi:[1,0]
	global_store_dwordx4 v166, v[130:133], s[30:31]
	v_rcp_f32_e32 v128, v128
	v_rcp_f32_e32 v129, v129
	v_pk_add_f32 v[132:133], v[140:141], 1.0 op_sel_hi:[1,0]
	v_rcp_f32_e32 v126, v126
	v_rcp_f32_e32 v127, v127
	v_rcp_f32_e32 v132, v132
	v_rcp_f32_e32 v133, v133
	v_pk_fma_f32 v[120:121], v[120:121], v[178:179], v[88:89] op_sel_hi:[1,0,1]
	v_pk_fma_f32 v[118:119], v[118:119], v[178:179], v[86:87] op_sel_hi:[1,0,1]
	v_pk_fma_f32 v[116:117], v[116:117], v[178:179], v[84:85] op_sel_hi:[1,0,1]
	v_pk_fma_f32 v[114:115], v[114:115], v[178:179], v[82:83] op_sel_hi:[1,0,1]
	v_pk_mul_f32 v[116:117], v[120:121], v[116:117]
	v_pk_mul_f32 v[114:115], v[118:119], v[114:115]
	v_pk_mul_f32 v[118:119], v[116:117], v[126:127]
	v_pk_mul_f32 v[116:117], v[114:115], v[128:129]
	v_pk_mul_f32 v[122:123], v[122:123], v[132:133]
	v_cvt_pk_bf16_f32 v116, v116, v117
	v_cvt_pk_bf16_f32 v117, v118, v119
	v_mul_f32_e32 v118, 0xbfb8aa3b, v168
	v_exp_f32_e32 v137, v135
	v_cvt_pk_bf16_f32 v114, v122, v123
	v_pk_fma_f32 v[122:123], v[110:111], v[118:119], v[156:157] op_sel_hi:[1,0,1]
	v_pk_mul_f32 v[120:121], v[112:113], v[118:119] op_sel_hi:[1,0]
	v_exp_f32_e32 v122, v122
	v_exp_f32_e32 v123, v123
	v_add_f32_e32 v119, v154, v120
	v_pk_add_f32 v[130:131], v[136:137], 1.0 op_sel_hi:[1,0]
	v_exp_f32_e32 v120, v119
	v_add_f32_e32 v119, v155, v121
	v_pk_fma_f32 v[112:113], v[112:113], v[168:169], v[104:105] op_sel_hi:[1,0,1]
	v_pk_fma_f32 v[110:111], v[110:111], v[168:169], v[102:103] op_sel_hi:[1,0,1]
	v_pk_fma_f32 v[108:109], v[108:109], v[168:169], v[100:101] op_sel_hi:[1,0,1]
	v_pk_fma_f32 v[106:107], v[106:107], v[168:169], v[98:99] op_sel_hi:[1,0,1]
	v_rcp_f32_e32 v130, v130
	v_rcp_f32_e32 v131, v131
	v_pk_mul_f32 v[106:107], v[110:111], v[106:107]
	v_pk_mul_f32 v[108:109], v[112:113], v[108:109]
	v_pk_fma_f32 v[110:111], v[96:97], v[118:119], v[150:151] op_sel_hi:[1,0,1]
	v_pk_fma_f32 v[112:113], v[94:95], v[118:119], v[152:153] op_sel_hi:[1,0,1]
	v_exp_f32_e32 v112, v112
	v_exp_f32_e32 v110, v110
	v_exp_f32_e32 v111, v111
	v_exp_f32_e32 v113, v113
	v_pk_mul_f32 v[124:125], v[124:125], v[130:131]
	s_mov_b32 s30, 0x2b000
	v_cvt_pk_bf16_f32 v115, v124, v125
	v_add_co_u32_e32 v124, vcc, s30, v146
	v_pk_add_f32 v[110:111], v[110:111], 1.0 op_sel_hi:[1,0]
	s_nop 0
	v_addc_co_u32_e32 v125, vcc, 0, v147, vcc
	v_pk_add_f32 v[112:113], v[112:113], 1.0 op_sel_hi:[1,0]
	global_store_dwordx4 v[124:125], v[114:117], off
	v_rcp_f32_e32 v112, v112
	v_rcp_f32_e32 v113, v113
	v_pk_add_f32 v[116:117], v[122:123], 1.0 op_sel_hi:[1,0]
	v_rcp_f32_e32 v110, v110
	v_rcp_f32_e32 v111, v111
	v_rcp_f32_e32 v116, v116
	v_rcp_f32_e32 v117, v117
;     template <int QVV> __device__ __forceinline__ void run(f32x4 (&acc)[2][2][4][2], const Unit& u, int wr, int wc, int fr, int fq) const {
;     ...
;             for (int m = 0; m < 4; ++m) { if (ai >= nai) continue;
;                 const float r = rs[ai][m], rn = r * (-LOG2E);
;                 f32x4 o[2];
; #pragma unroll
;                 for (int n = 0; n < 2; ++n) {
;                     const f32x4 gt = acc[ai][0][m][n] * r + sg[n], up = acc[ai][1][m][n] * r + su[n], ex = acc[ai][0][m][n] * rn + sgn[n];
;                     f32x4 den, rc;
; #pragma unroll
;                     for (int i = 0; i < 4; ++i) den[i] = __builtin_amdgcn_exp2f(ex[i]);
;                     den = den + 1.0f;
; #pragma unroll
;                     for (int i = 0; i < 4; ++i) rc[i] = __builtin_amdgcn_rcpf(den[i]);
;                     o[n] = (gt * up) * rc; }
;                 u32x4 w; w.x = pk2(o[0][0], o[0][1]); w.y = pk2(o[0][2], o[0][3]); w.z = pk2(o[1][0], o[1][1]); w.w = pk2(o[1][2], o[1][3]);
;                 *(u32x4*)(tb + lo + (unsigned)(ai * HALF + m * 16) * (DFF * 2)) = w; }
	v_pk_fma_f32 v[96:97], v[96:97], v[168:169], v[88:89] op_sel_hi:[1,0,1]
	v_pk_fma_f32 v[94:95], v[94:95], v[168:169], v[86:87] op_sel_hi:[1,0,1]
	v_pk_fma_f32 v[92:93], v[92:93], v[168:169], v[84:85] op_sel_hi:[1,0,1]
	v_pk_fma_f32 v[90:91], v[90:91], v[168:169], v[82:83] op_sel_hi:[1,0,1]
	v_pk_mul_f32 v[92:93], v[96:97], v[92:93]
	v_pk_mul_f32 v[90:91], v[94:95], v[90:91]
	v_pk_mul_f32 v[94:95], v[92:93], v[110:111]
	v_pk_mul_f32 v[92:93], v[90:91], v[112:113]
	v_pk_mul_f32 v[106:107], v[106:107], v[116:117]
	v_cvt_pk_bf16_f32 v92, v92, v93
	v_cvt_pk_bf16_f32 v93, v94, v95
	v_mul_f32_e32 v94, 0xbfb8aa3b, v164
	v_exp_f32_e32 v121, v119
	v_cvt_pk_bf16_f32 v90, v106, v107
	v_pk_fma_f32 v[106:107], v[78:79], v[94:95], v[156:157] op_sel_hi:[1,0,1]
	v_pk_mul_f32 v[96:97], v[80:81], v[94:95] op_sel_hi:[1,0]
	v_exp_f32_e32 v106, v106
	v_exp_f32_e32 v107, v107
	v_add_f32_e32 v95, v154, v96
	v_pk_add_f32 v[114:115], v[120:121], 1.0 op_sel_hi:[1,0]
	v_exp_f32_e32 v96, v95
	v_add_f32_e32 v95, v155, v97
	v_pk_fma_f32 v[80:81], v[80:81], v[164:165], v[104:105] op_sel_hi:[1,0,1]
	v_pk_fma_f32 v[78:79], v[78:79], v[164:165], v[102:103] op_sel_hi:[1,0,1]
	v_pk_fma_f32 v[76:77], v[76:77], v[164:165], v[100:101] op_sel_hi:[1,0,1]
	v_pk_fma_f32 v[74:75], v[74:75], v[164:165], v[98:99] op_sel_hi:[1,0,1]
	v_rcp_f32_e32 v114, v114
	v_rcp_f32_e32 v115, v115
	v_pk_mul_f32 v[74:75], v[78:79], v[74:75]
	v_pk_mul_f32 v[76:77], v[80:81], v[76:77]
	v_pk_fma_f32 v[78:79], v[72:73], v[94:95], v[150:151] op_sel_hi:[1,0,1]
	v_pk_fma_f32 v[80:81], v[70:71], v[94:95], v[152:153] op_sel_hi:[1,0,1]
	v_exp_f32_e32 v80, v80
	v_exp_f32_e32 v78, v78
	v_exp_f32_e32 v79, v79
	v_exp_f32_e32 v81, v81
	v_pk_mul_f32 v[108:109], v[108:109], v[114:115]
	s_mov_b32 s30, 0x56000
	v_cvt_pk_bf16_f32 v91, v108, v109
	v_add_co_u32_e32 v108, vcc, s30, v146
	v_pk_add_f32 v[78:79], v[78:79], 1.0 op_sel_hi:[1,0]
	s_nop 0
	v_addc_co_u32_e32 v109, vcc, 0, v147, vcc
	v_pk_add_f32 v[80:81], v[80:81], 1.0 op_sel_hi:[1,0]
	global_store_dwordx4 v[108:109], v[90:93], off
	v_rcp_f32_e32 v80, v80
	v_rcp_f32_e32 v81, v81
	v_pk_add_f32 v[92:93], v[106:107], 1.0 op_sel_hi:[1,0]
	v_rcp_f32_e32 v78, v78
	v_rcp_f32_e32 v79, v79
	v_rcp_f32_e32 v92, v92
	v_rcp_f32_e32 v93, v93
	v_pk_fma_f32 v[72:73], v[72:73], v[164:165], v[88:89] op_sel_hi:[1,0,1]
	v_pk_fma_f32 v[70:71], v[70:71], v[164:165], v[86:87] op_sel_hi:[1,0,1]
	v_pk_fma_f32 v[68:69], v[68:69], v[164:165], v[84:85] op_sel_hi:[1,0,1]
	v_pk_fma_f32 v[66:67], v[66:67], v[164:165], v[82:83] op_sel_hi:[1,0,1]
	v_pk_mul_f32 v[68:69], v[72:73], v[68:69]
	v_pk_mul_f32 v[66:67], v[70:71], v[66:67]
	v_pk_mul_f32 v[70:71], v[68:69], v[78:79]
	v_pk_mul_f32 v[68:69], v[66:67], v[80:81]
	v_pk_mul_f32 v[74:75], v[74:75], v[92:93]
	v_cvt_pk_bf16_f32 v68, v68, v69
	v_cvt_pk_bf16_f32 v69, v70, v71
	v_mul_f32_e32 v70, 0xbfb8aa3b, v162
	v_exp_f32_e32 v97, v95
	v_cvt_pk_bf16_f32 v66, v74, v75
	v_pk_fma_f32 v[74:75], v[62:63], v[70:71], v[156:157] op_sel_hi:[1,0,1]
	v_pk_mul_f32 v[72:73], v[64:65], v[70:71] op_sel_hi:[1,0]
	v_exp_f32_e32 v74, v74
	v_exp_f32_e32 v75, v75
	v_add_f32_e32 v71, v154, v72
	v_pk_add_f32 v[90:91], v[96:97], 1.0 op_sel_hi:[1,0]
	v_exp_f32_e32 v72, v71
	v_add_f32_e32 v71, v155, v73
	v_pk_fma_f32 v[64:65], v[64:65], v[162:163], v[104:105] op_sel_hi:[1,0,1]
	v_pk_fma_f32 v[62:63], v[62:63], v[162:163], v[102:103] op_sel_hi:[1,0,1]
	v_pk_fma_f32 v[60:61], v[60:61], v[162:163], v[100:101] op_sel_hi:[1,0,1]
	v_pk_fma_f32 v[58:59], v[58:59], v[162:163], v[98:99] op_sel_hi:[1,0,1]
	v_rcp_f32_e32 v90, v90
	v_rcp_f32_e32 v91, v91
	v_pk_mul_f32 v[58:59], v[62:63], v[58:59]
	v_pk_mul_f32 v[60:61], v[64:65], v[60:61]
	v_pk_fma_f32 v[62:63], v[56:57], v[70:71], v[150:151] op_sel_hi:[1,0,1]
	v_pk_fma_f32 v[64:65], v[54:55], v[70:71], v[152:153] op_sel_hi:[1,0,1]
	v_exp_f32_e32 v64, v64
	v_exp_f32_e32 v62, v62
	v_exp_f32_e32 v63, v63
	v_exp_f32_e32 v65, v65
	v_pk_mul_f32 v[76:77], v[76:77], v[90:91]
	s_mov_b32 s30, 0x81000
	v_cvt_pk_bf16_f32 v67, v76, v77
	v_add_co_u32_e32 v76, vcc, s30, v146
	v_pk_add_f32 v[62:63], v[62:63], 1.0 op_sel_hi:[1,0]
	s_nop 0
	v_addc_co_u32_e32 v77, vcc, 0, v147, vcc
	v_pk_add_f32 v[64:65], v[64:65], 1.0 op_sel_hi:[1,0]
	global_store_dwordx4 v[76:77], v[66:69], off
	v_rcp_f32_e32 v64, v64
	v_rcp_f32_e32 v65, v65
	v_pk_add_f32 v[68:69], v[74:75], 1.0 op_sel_hi:[1,0]
	v_rcp_f32_e32 v62, v62
	v_rcp_f32_e32 v63, v63
	v_rcp_f32_e32 v68, v68
	v_rcp_f32_e32 v69, v69
	v_pk_fma_f32 v[56:57], v[56:57], v[162:163], v[88:89] op_sel_hi:[1,0,1]
	v_pk_fma_f32 v[54:55], v[54:55], v[162:163], v[86:87] op_sel_hi:[1,0,1]
	v_pk_fma_f32 v[52:53], v[52:53], v[162:163], v[84:85] op_sel_hi:[1,0,1]
	v_pk_fma_f32 v[50:51], v[50:51], v[162:163], v[82:83] op_sel_hi:[1,0,1]
	v_pk_mul_f32 v[52:53], v[56:57], v[52:53]
	v_pk_mul_f32 v[50:51], v[54:55], v[50:51]
	v_pk_mul_f32 v[54:55], v[52:53], v[62:63]
	v_pk_mul_f32 v[52:53], v[50:51], v[64:65]
	v_pk_mul_f32 v[58:59], v[58:59], v[68:69]
	v_cvt_pk_bf16_f32 v52, v52, v53
	v_cvt_pk_bf16_f32 v53, v54, v55
	v_mul_f32_e32 v54, 0xbfb8aa3b, v160
	v_exp_f32_e32 v73, v71
	v_cvt_pk_bf16_f32 v50, v58, v59
	v_pk_fma_f32 v[58:59], v[46:47], v[54:55], v[156:157] op_sel_hi:[1,0,1]
	v_pk_mul_f32 v[56:57], v[48:49], v[54:55] op_sel_hi:[1,0]
	v_exp_f32_e32 v58, v58
	v_exp_f32_e32 v59, v59
	v_add_f32_e32 v55, v154, v56
	v_pk_add_f32 v[66:67], v[72:73], 1.0 op_sel_hi:[1,0]
	v_exp_f32_e32 v56, v55
	v_add_f32_e32 v55, v155, v57
	v_pk_fma_f32 v[48:49], v[48:49], v[160:161], v[104:105] op_sel_hi:[1,0,1]
	v_pk_fma_f32 v[46:47], v[46:47], v[160:161], v[102:103] op_sel_hi:[1,0,1]
	v_pk_fma_f32 v[44:45], v[44:45], v[160:161], v[100:101] op_sel_hi:[1,0,1]
;     template <int QVV> __device__ __forceinline__ void run(f32x4 (&acc)[2][2][4][2], const Unit& u, int wr, int wc, int fr, int fq) const {
;     ...
; #pragma unroll
;         for (int ai = 0; ai < 2; ++ai)
; #pragma unroll
;             for (int m = 0; m < 4; ++m) { if (ai >= nai) continue;
;                 const float r = rs[ai][m], rn = r * (-LOG2E);
;                 f32x4 o[2];
; #pragma unroll
;                 for (int n = 0; n < 2; ++n) {
;                     const f32x4 gt = acc[ai][0][m][n] * r + sg[n], up = acc[ai][1][m][n] * r + su[n], ex = acc[ai][0][m][n] * rn + sgn[n];
;                     f32x4 den, rc;
; #pragma unroll
;                     for (int i = 0; i < 4; ++i) den[i] = __builtin_amdgcn_exp2f(ex[i]);
;                     den = den + 1.0f;
; #pragma unroll
;                     for (int i = 0; i < 4; ++i) rc[i] = __builtin_amdgcn_rcpf(den[i]);
;                     o[n] = (gt * up) * rc; }
;                 u32x4 w; w.x = pk2(o[0][0], o[0][1]); w.y = pk2(o[0][2], o[0][3]); w.z = pk2(o[1][0], o[1][1]); w.w = pk2(o[1][2], o[1][3]);
;                 *(u32x4*)(tb + lo + (unsigned)(ai * HALF + m * 16) * (DFF * 2)) = w; }
	v_pk_fma_f32 v[42:43], v[42:43], v[160:161], v[98:99] op_sel_hi:[1,0,1]
	v_rcp_f32_e32 v66, v66
	v_rcp_f32_e32 v67, v67
	v_pk_mul_f32 v[42:43], v[46:47], v[42:43]
	v_pk_mul_f32 v[44:45], v[48:49], v[44:45]
	v_pk_fma_f32 v[46:47], v[40:41], v[54:55], v[150:151] op_sel_hi:[1,0,1]
	v_pk_fma_f32 v[48:49], v[38:39], v[54:55], v[152:153] op_sel_hi:[1,0,1]
	v_exp_f32_e32 v48, v48
	v_exp_f32_e32 v46, v46
	v_exp_f32_e32 v47, v47
	v_exp_f32_e32 v49, v49
	v_pk_mul_f32 v[60:61], v[60:61], v[66:67]
	s_mov_b32 s30, 0x158000
	v_cvt_pk_bf16_f32 v51, v60, v61
	v_add_co_u32_e32 v60, vcc, s30, v146
	v_pk_add_f32 v[46:47], v[46:47], 1.0 op_sel_hi:[1,0]
	s_nop 0
	v_addc_co_u32_e32 v61, vcc, 0, v147, vcc
	v_pk_add_f32 v[48:49], v[48:49], 1.0 op_sel_hi:[1,0]
	global_store_dwordx4 v[60:61], v[50:53], off
	v_rcp_f32_e32 v48, v48
	v_rcp_f32_e32 v49, v49
	v_pk_add_f32 v[52:53], v[58:59], 1.0 op_sel_hi:[1,0]
	v_rcp_f32_e32 v46, v46
	v_rcp_f32_e32 v47, v47
	v_rcp_f32_e32 v52, v52
	v_rcp_f32_e32 v53, v53
	v_pk_fma_f32 v[40:41], v[40:41], v[160:161], v[88:89] op_sel_hi:[1,0,1]
	v_pk_fma_f32 v[38:39], v[38:39], v[160:161], v[86:87] op_sel_hi:[1,0,1]
	v_pk_fma_f32 v[36:37], v[36:37], v[160:161], v[84:85] op_sel_hi:[1,0,1]
	v_pk_fma_f32 v[34:35], v[34:35], v[160:161], v[82:83] op_sel_hi:[1,0,1]
	v_pk_mul_f32 v[36:37], v[40:41], v[36:37]
	v_pk_mul_f32 v[34:35], v[38:39], v[34:35]
	v_pk_mul_f32 v[38:39], v[36:37], v[46:47]
	v_pk_mul_f32 v[36:37], v[34:35], v[48:49]
	v_pk_mul_f32 v[42:43], v[42:43], v[52:53]
	v_cvt_pk_bf16_f32 v36, v36, v37
	v_cvt_pk_bf16_f32 v37, v38, v39
	v_mul_f32_e32 v38, 0xbfb8aa3b, v158
	v_exp_f32_e32 v57, v55
	v_cvt_pk_bf16_f32 v34, v42, v43
	v_pk_fma_f32 v[42:43], v[30:31], v[38:39], v[156:157] op_sel_hi:[1,0,1]
	v_pk_mul_f32 v[40:41], v[32:33], v[38:39] op_sel_hi:[1,0]
	v_exp_f32_e32 v42, v42
	v_exp_f32_e32 v43, v43
	v_add_f32_e32 v39, v154, v40
	v_pk_add_f32 v[50:51], v[56:57], 1.0 op_sel_hi:[1,0]
	v_exp_f32_e32 v40, v39
	v_add_f32_e32 v39, v155, v41
	v_pk_fma_f32 v[32:33], v[32:33], v[158:159], v[104:105] op_sel_hi:[1,0,1]
	v_pk_fma_f32 v[30:31], v[30:31], v[158:159], v[102:103] op_sel_hi:[1,0,1]
	v_pk_fma_f32 v[28:29], v[28:29], v[158:159], v[100:101] op_sel_hi:[1,0,1]
	v_pk_fma_f32 v[26:27], v[26:27], v[158:159], v[98:99] op_sel_hi:[1,0,1]
	v_rcp_f32_e32 v50, v50
	v_rcp_f32_e32 v51, v51
	v_pk_mul_f32 v[26:27], v[30:31], v[26:27]
	v_pk_mul_f32 v[28:29], v[32:33], v[28:29]
	v_pk_fma_f32 v[30:31], v[24:25], v[38:39], v[150:151] op_sel_hi:[1,0,1]
	v_pk_fma_f32 v[32:33], v[22:23], v[38:39], v[152:153] op_sel_hi:[1,0,1]
	v_exp_f32_e32 v32, v32
	v_exp_f32_e32 v30, v30
	v_exp_f32_e32 v31, v31
	v_exp_f32_e32 v33, v33
	v_pk_mul_f32 v[44:45], v[44:45], v[50:51]
	s_mov_b32 s30, 0x183000
	v_cvt_pk_bf16_f32 v35, v44, v45
	v_add_co_u32_e32 v44, vcc, s30, v146
	v_pk_add_f32 v[30:31], v[30:31], 1.0 op_sel_hi:[1,0]
	s_nop 0
	v_addc_co_u32_e32 v45, vcc, 0, v147, vcc
	v_pk_add_f32 v[32:33], v[32:33], 1.0 op_sel_hi:[1,0]
	v_fmamk_f32 v148, v188, 0x30000000, v231
	global_store_dwordx4 v[44:45], v[34:37], off
	v_rcp_f32_e32 v32, v32
	v_rcp_f32_e32 v33, v33
	v_pk_add_f32 v[36:37], v[42:43], 1.0 op_sel_hi:[1,0]
	v_rcp_f32_e32 v30, v30
	v_rcp_f32_e32 v31, v31
	v_rsq_f32_e32 v148, v148
	v_rcp_f32_e32 v36, v36
	v_rcp_f32_e32 v37, v37
	v_pk_fma_f32 v[24:25], v[24:25], v[158:159], v[88:89] op_sel_hi:[1,0,1]
	v_pk_fma_f32 v[22:23], v[22:23], v[158:159], v[86:87] op_sel_hi:[1,0,1]
	v_pk_fma_f32 v[20:21], v[20:21], v[158:159], v[84:85] op_sel_hi:[1,0,1]
	v_pk_fma_f32 v[18:19], v[18:19], v[158:159], v[82:83] op_sel_hi:[1,0,1]
	v_pk_mul_f32 v[20:21], v[24:25], v[20:21]
	v_pk_mul_f32 v[18:19], v[22:23], v[18:19]
	v_pk_mul_f32 v[22:23], v[20:21], v[30:31]
	v_pk_mul_f32 v[20:21], v[18:19], v[32:33]
	v_pk_mul_f32 v[26:27], v[26:27], v[36:37]
	v_cvt_pk_bf16_f32 v20, v20, v21
	v_cvt_pk_bf16_f32 v21, v22, v23
	v_mul_f32_e32 v22, 0xbfb8aa3b, v148
	v_cvt_pk_bf16_f32 v18, v26, v27
	v_pk_fma_f32 v[26:27], v[14:15], v[22:23], v[156:157] op_sel_hi:[1,0,1]
	v_exp_f32_e32 v41, v39
	v_pk_mul_f32 v[24:25], v[16:17], v[22:23] op_sel_hi:[1,0]
	v_exp_f32_e32 v26, v26
	v_exp_f32_e32 v27, v27
	v_add_f32_e32 v23, v154, v24
	v_exp_f32_e32 v24, v23
	v_add_f32_e32 v23, v155, v25
	v_pk_fma_f32 v[16:17], v[16:17], v[148:149], v[104:105] op_sel_hi:[1,0,1]
	v_pk_fma_f32 v[14:15], v[14:15], v[148:149], v[102:103] op_sel_hi:[1,0,1]
	v_pk_fma_f32 v[12:13], v[12:13], v[148:149], v[100:101] op_sel_hi:[1,0,1]
	v_pk_fma_f32 v[10:11], v[10:11], v[148:149], v[98:99] op_sel_hi:[1,0,1]
	v_pk_add_f32 v[34:35], v[40:41], 1.0 op_sel_hi:[1,0]
	v_pk_mul_f32 v[10:11], v[14:15], v[10:11]
	v_pk_mul_f32 v[12:13], v[16:17], v[12:13]
	v_pk_fma_f32 v[14:15], v[8:9], v[22:23], v[150:151] op_sel_hi:[1,0,1]
	v_pk_fma_f32 v[16:17], v[6:7], v[22:23], v[152:153] op_sel_hi:[1,0,1]
	v_rcp_f32_e32 v34, v34
	v_rcp_f32_e32 v35, v35
	v_exp_f32_e32 v16, v16
	v_exp_f32_e32 v14, v14
	v_exp_f32_e32 v15, v15
	v_exp_f32_e32 v17, v17
	v_exp_f32_e32 v25, v23
	v_pk_mul_f32 v[28:29], v[28:29], v[34:35]
	s_mov_b32 s30, 0x1ae000
	v_cvt_pk_bf16_f32 v19, v28, v29
	v_add_co_u32_e32 v28, vcc, s30, v146
	v_pk_add_f32 v[14:15], v[14:15], 1.0 op_sel_hi:[1,0]
	v_pk_add_f32 v[16:17], v[16:17], 1.0 op_sel_hi:[1,0]
	v_addc_co_u32_e32 v29, vcc, 0, v147, vcc
	v_rcp_f32_e32 v16, v16
	v_rcp_f32_e32 v17, v17
	v_rcp_f32_e32 v14, v14
	v_rcp_f32_e32 v15, v15
	global_store_dwordx4 v[28:29], v[18:21], off
	v_pk_fma_f32 v[8:9], v[8:9], v[148:149], v[88:89] op_sel_hi:[1,0,1]
	v_pk_fma_f32 v[6:7], v[6:7], v[148:149], v[86:87] op_sel_hi:[1,0,1]
	v_pk_add_f32 v[18:19], v[24:25], 1.0 op_sel_hi:[1,0]
	v_pk_add_f32 v[20:21], v[26:27], 1.0 op_sel_hi:[1,0]
	v_rcp_f32_e32 v18, v18
	v_rcp_f32_e32 v20, v20
	v_rcp_f32_e32 v21, v21
	v_rcp_f32_e32 v19, v19
	v_pk_fma_f32 v[4:5], v[4:5], v[148:149], v[84:85] op_sel_hi:[1,0,1]
	v_pk_fma_f32 v[2:3], v[2:3], v[148:149], v[82:83] op_sel_hi:[1,0,1]
	v_pk_mul_f32 v[4:5], v[8:9], v[4:5]
	v_pk_mul_f32 v[2:3], v[6:7], v[2:3]
	v_pk_mul_f32 v[6:7], v[4:5], v[14:15]
	v_pk_mul_f32 v[4:5], v[2:3], v[16:17]
	v_pk_mul_f32 v[12:13], v[12:13], v[18:19]
	v_cvt_pk_bf16_f32 v4, v4, v5
	v_cvt_pk_bf16_f32 v5, v6, v7
	v_add_co_u32_e32 v6, vcc, 0x1d9000, v146
	v_pk_mul_f32 v[10:11], v[10:11], v[20:21]
	s_nop 0
	v_addc_co_u32_e32 v7, vcc, 0, v147, vcc
	v_cvt_pk_bf16_f32 v2, v10, v11
	v_cvt_pk_bf16_f32 v3, v12, v13
	s_andn2_b64 vcc, exec, s[38:39]
	s_mov_b64 s[30:31], -1
	global_store_dwordx4 v[6:7], v[2:5], off
	s_cbranch_vccnz .LBB0_1643
	s_andn2_b64 vcc, exec, s[46:47]
	v_mov_b64 v[2:3], 0
	v_mov_b64 v[4:5], 0
	s_cbranch_vccnz .LBB0_1642
	s_barrier
	s_branch .LBB0_1642

; __device__ __forceinline__ void row_rstd(const unsigned long long* ssq, int row0, float (&rs)[2][4]) {
;     unsigned long long q[2][4];
; #pragma unroll
;     for (int ai = 0; ai < 2; ++ai)
; #pragma unroll
;         for (int m = 0; m < 4; ++m) q[ai][m] = ssq[row0 + ai * HALF + m * 16];
;     asm volatile("" : "+v"(q[0][0]), "+v"(q[0][1]), "+v"(q[0][2]), "+v"(q[0][3]), "+v"(q[1][0]), "+v"(q[1][1]), "+v"(q[1][2]), "+v"(q[1][3]));
;     template <int QVV> __device__ __forceinline__ void run(f32x4 (&acc)[2][2][4][2], const Unit& u, int wr, int wc, int fr, int fq) const {
;         constexpr int nai = (QVV == 2) ? 1 : 2; const int r0 = u.pm * BM + (QVV == 2 ? (u.seg - 1) * HALF : 0);
;         char* tb = (char*)(O + (size_t)r0 * DFF + u.pn * HALF);
;         const int v = u.pm < 4 ? 4 : ((u.pm - 4) >> 5);
;         const char* swb = (const char*)(sw + (size_t)v * SWLD + u.pn * BM);
;         unsigned lo = (unsigned)((wr * 64 + fr) * DFF + wc * 32 + 8 * fq) * 2u;
;         unsigned co = (unsigned)(wc * 32 + 8 * fq) * 4u;
;         asm volatile("" : "+v"(lo), "+v"(co));
;         float rs[2][4]; row_rstd(ssq, r0 + wr * 64 + fr, rs);
;         f32x4 sg[2], su[2], sgn[2];
; #pragma unroll
;         for (int n = 0; n < 2; ++n) { sg[n] = *(const f32x4*)(swb + co + n * 16); su[n] = *(const f32x4*)(swb + co + HALF * 4 + n * 16); sgn[n] = sg[n] * (-LOG2E); }
; #pragma unroll
;         for (int ai = 0; ai < 2; ++ai)
; #pragma unroll
;             for (int m = 0; m < 4; ++m) { if (ai >= nai) continue;
;                 const float r = rs[ai][m], rn = r * (-LOG2E);
;                 f32x4 o[2];
; #pragma unroll
;                 for (int n = 0; n < 2; ++n) {
;                     const f32x4 gt = acc[ai][0][m][n] * r + sg[n], up = acc[ai][1][m][n] * r + su[n], ex = acc[ai][0][m][n] * rn + sgn[n];
;                     f32x4 den, rc;
; #pragma unroll
;                     for (int i = 0; i < 4; ++i) den[i] = __builtin_amdgcn_exp2f(ex[i]);
;                     den = den + 1.0f;
; #pragma unroll
;                     for (int i = 0; i < 4; ++i) rc[i] = __builtin_amdgcn_rcpf(den[i]);
;                     o[n] = (gt * up) * rc; }
;                 u32x4 w; w.x = pk2(o[0][0], o[0][1]); w.y = pk2(o[0][2], o[0][3]); w.z = pk2(o[1][0], o[1][1]); w.w = pk2(o[1][2], o[1][3]);
;                 *(u32x4*)(tb + lo + (unsigned)(ai * HALF + m * 16) * (DFF * 2)) = w; }
.LBB0_1673:
	s_movk_i32 s10, 0x1580
	v_mul_lo_u32 v66, v70, s10
	s_lshl_b32 s8, s8, 8
	v_readlane_b32 s10, v253, 9
	v_or3_b32 v66, v66, v71, s19
	s_or_b32 s8, s8, s10
	v_or_b32_e32 v67, s19, v71
	v_lshlrev_b32_e32 v86, 1, v66
	v_add_u32_e32 v66, s8, v70
	v_lshlrev_b32_e32 v82, 2, v67
	v_ashrrev_i32_e32 v67, 31, v66
	v_lshl_add_u64 v[66:67], v[66:67], 3, s[34:35]
	global_load_dwordx2 v[84:85], v[66:67], off
	global_load_dwordx2 v[88:89], v[66:67], off offset:128
	global_load_dwordx2 v[90:91], v[66:67], off offset:256
	global_load_dwordx2 v[92:93], v[66:67], off offset:384
	global_load_dwordx2 v[68:69], v[66:67], off offset:1024
	global_load_dwordx2 v[70:71], v[66:67], off offset:1152
	global_load_dwordx2 v[72:73], v[66:67], off offset:1280
	s_nop 0
	global_load_dwordx2 v[66:67], v[66:67], off offset:1408
	s_mul_hi_i32 s10, s8, 0x2b00
	s_mulk_i32 s8, 0x2b00
	s_add_u32 s8, s2, s8
	s_addc_u32 s10, s3, s10
	s_lshl_b32 s2, s9, 7
	s_ashr_i32 s3, s2, 31
	s_lshl_b64 s[2:3], s[2:3], 1
	s_add_u32 s30, s8, s2
	s_addc_u32 s31, s10, s3
	s_lshl_b64 s[2:3], s[38:39], 2
	s_add_u32 s5, s5, s2
	s_addc_u32 s7, s7, s3
	s_lshl_b32 s2, s9, 8
	s_ashr_i32 s3, s2, 31
	s_lshl_b64 s[2:3], s[2:3], 2
	s_add_u32 s2, s5, s2
	s_addc_u32 s3, s7, s3
	v_mov_b32_e32 v87, v175
	s_waitcnt vmcnt(0)
	global_load_dwordx4 v[78:81], v82, s[2:3]
	global_load_dwordx4 v[70:73], v82, s[2:3] offset:16
	global_load_dwordx4 v[74:77], v82, s[2:3] offset:512
	global_load_dwordx4 v[66:69], v82, s[2:3] offset:528
	s_flbit_i32_b32 s2, 0
	s_min_u32 s2, s2, 32
	v_mov_b32_e32 v174, v89
	v_lshl_add_u64 v[82:83], s[30:31], 0, v[86:87]
	v_cvt_f32_u32_e32 v87, v88
	v_lshlrev_b64 v[88:89], s2, v[174:175]
	v_mov_b32_e32 v174, v91
	v_cvt_f32_u32_e32 v95, v90
	v_cvt_f32_u32_e32 v96, v84
	v_min_u32_e32 v84, 1, v88
	v_lshlrev_b64 v[90:91], s2, v[174:175]
	v_mov_b32_e32 v174, v93
	v_or_b32_e32 v84, v89, v84
	v_min_u32_e32 v90, 1, v90
	v_lshlrev_b64 v[88:89], s2, v[174:175]
	v_mov_b32_e32 v174, v85
	v_cvt_f32_u32_e32 v93, v84
	v_or_b32_e32 v90, v91, v90
	v_min_u32_e32 v88, 1, v88
	v_lshlrev_b64 v[84:85], s2, v[174:175]
	v_cvt_f32_u32_e32 v90, v90
	v_or_b32_e32 v88, v89, v88
	v_min_u32_e32 v84, 1, v84
	v_cvt_f32_u32_e32 v88, v88
	v_or_b32_e32 v84, v85, v84
	s_sub_i32 s3, 32, s2
	v_cvt_f32_u32_e32 v92, v92
	v_cvt_f32_u32_e32 v84, v84
	v_ldexp_f32 v85, v93, s3
	v_fmac_f32_e32 v87, 0x4f800000, v85
	v_ldexp_f32 v85, v90, s3
	v_fmac_f32_e32 v95, 0x4f800000, v85
	v_ldexp_f32 v85, v88, s3
	v_fmac_f32_e32 v92, 0x4f800000, v85
	v_ldexp_f32 v84, v84, s3
	v_fmamk_f32 v87, v87, 0x30000000, v231
	v_fmamk_f32 v85, v92, 0x30000000, v231
	v_fmac_f32_e32 v96, 0x4f800000, v84
	v_rsq_f32_e32 v94, v87
	v_rsq_f32_e32 v84, v85
	v_fmamk_f32 v85, v96, 0x30000000, v231
	v_rsq_f32_e32 v96, v85
	v_mul_f32_e32 v90, 0xbfb8aa3b, v94
	v_pk_mul_f32 v[98:99], v[56:57], v[90:91] op_sel_hi:[1,0]
	v_pk_mul_f32 v[100:101], v[54:55], v[90:91] op_sel_hi:[1,0]
	v_pk_mul_f32 v[102:103], v[40:41], v[90:91] op_sel_hi:[1,0]
	v_pk_mul_f32 v[104:105], v[38:39], v[90:91] op_sel_hi:[1,0]
	v_mul_f32_e32 v90, 0xbfb8aa3b, v96
	s_mov_b32 s2, 0xbfb8aa3b
	v_fmamk_f32 v87, v95, 0x30000000, v231
	v_pk_mul_f32 v[106:107], v[64:65], v[90:91] op_sel_hi:[1,0]
	v_pk_mul_f32 v[108:109], v[62:63], v[90:91] op_sel_hi:[1,0]
	v_pk_mul_f32 v[110:111], v[60:61], v[90:91] op_sel_hi:[1,0]
	v_pk_mul_f32 v[112:113], v[58:59], v[90:91] op_sel_hi:[1,0]
	v_rsq_f32_e32 v88, v87
	s_waitcnt vmcnt(3)
	v_pk_mul_f32 v[114:115], v[80:81], s[2:3] op_sel_hi:[1,0]
	v_pk_mul_f32 v[116:117], v[78:79], s[2:3] op_sel_hi:[1,0]
	s_waitcnt vmcnt(2)
	v_pk_mul_f32 v[90:91], v[72:73], s[2:3] op_sel_hi:[1,0]
	v_pk_mul_f32 v[92:93], v[70:71], s[2:3] op_sel_hi:[1,0]
	v_pk_fma_f32 v[64:65], v[64:65], v[96:97], v[80:81] op_sel_hi:[1,0,1]
	v_pk_fma_f32 v[62:63], v[62:63], v[96:97], v[78:79] op_sel_hi:[1,0,1]
	s_waitcnt vmcnt(1)
	v_pk_fma_f32 v[52:53], v[52:53], v[96:97], v[76:77] op_sel_hi:[1,0,1]
	v_pk_fma_f32 v[50:51], v[50:51], v[96:97], v[74:75] op_sel_hi:[1,0,1]
	v_pk_fma_f32 v[60:61], v[60:61], v[96:97], v[72:73] op_sel_hi:[1,0,1]
	v_pk_fma_f32 v[58:59], v[58:59], v[96:97], v[70:71] op_sel_hi:[1,0,1]
	s_waitcnt vmcnt(0)
	v_pk_fma_f32 v[48:49], v[48:49], v[96:97], v[68:69] op_sel_hi:[1,0,1]
	v_pk_fma_f32 v[46:47], v[46:47], v[96:97], v[66:67] op_sel_hi:[1,0,1]
	v_pk_fma_f32 v[56:57], v[56:57], v[94:95], v[80:81] op_sel_hi:[1,0,1]
	v_pk_fma_f32 v[54:55], v[54:55], v[94:95], v[78:79] op_sel_hi:[1,0,1]
	v_pk_fma_f32 v[44:45], v[44:45], v[94:95], v[76:77] op_sel_hi:[1,0,1]
	v_pk_fma_f32 v[42:43], v[42:43], v[94:95], v[74:75] op_sel_hi:[1,0,1]
	v_add_f32_e32 v85, v116, v108
	v_add_f32_e32 v87, v117, v109
	v_add_f32_e32 v89, v114, v106
	v_add_f32_e32 v95, v115, v107
	v_pk_mul_f32 v[50:51], v[62:63], v[50:51]
	v_pk_mul_f32 v[52:53], v[64:65], v[52:53]
	v_add_f32_e32 v62, v92, v112
	v_add_f32_e32 v63, v93, v113
	v_add_f32_e32 v64, v90, v110
	v_add_f32_e32 v65, v91, v111
	v_pk_mul_f32 v[46:47], v[58:59], v[46:47]
	v_pk_mul_f32 v[48:49], v[60:61], v[48:49]
	v_add_f32_e32 v96, v116, v100
	v_add_f32_e32 v97, v117, v101
	v_add_f32_e32 v98, v114, v98
	v_add_f32_e32 v99, v115, v99
	v_pk_mul_f32 v[42:43], v[54:55], v[42:43]
	v_pk_mul_f32 v[44:45], v[56:57], v[44:45]
	v_exp_f32_e32 v54, v85
	v_exp_f32_e32 v55, v87
	v_exp_f32_e32 v56, v89
	v_exp_f32_e32 v57, v95
	v_exp_f32_e32 v58, v62
	v_exp_f32_e32 v59, v63
	v_exp_f32_e32 v60, v64
	v_exp_f32_e32 v61, v65
	v_exp_f32_e32 v62, v96
	v_exp_f32_e32 v63, v97
	v_exp_f32_e32 v64, v98
	v_exp_f32_e32 v65, v99
	v_pk_add_f32 v[56:57], v[56:57], 1.0 op_sel_hi:[1,0]
	v_pk_add_f32 v[54:55], v[54:55], 1.0 op_sel_hi:[1,0]
	v_pk_add_f32 v[60:61], v[60:61], 1.0 op_sel_hi:[1,0]
; #define PG8_WAIT_V(n) asm volatile("s_waitcnt vmcnt(" #n ")" ::: "memory")
; #define PG8_BAR __builtin_amdgcn_s_barrier()
;     ...
;     PG8_WAIT_V(0);
;     PG8_BAR;
;     template <int QVV> __device__ __forceinline__ void run(f32x4 (&acc)[2][2][4][2], const Unit& u, int wr, int wc, int fr, int fq) const {
;     ...
; #pragma unroll
;         for (int ai = 0; ai < 2; ++ai)
; #pragma unroll
;             for (int m = 0; m < 4; ++m) { if (ai >= nai) continue;
;                 const float r = rs[ai][m], rn = r * (-LOG2E);
;                 f32x4 o[2];
; #pragma unroll
;                 for (int n = 0; n < 2; ++n) {
;                     const f32x4 gt = acc[ai][0][m][n] * r + sg[n], up = acc[ai][1][m][n] * r + su[n], ex = acc[ai][0][m][n] * rn + sgn[n];
;                     f32x4 den, rc;
; #pragma unroll
;                     for (int i = 0; i < 4; ++i) den[i] = __builtin_amdgcn_exp2f(ex[i]);
;                     den = den + 1.0f;
; #pragma unroll
;                     for (int i = 0; i < 4; ++i) rc[i] = __builtin_amdgcn_rcpf(den[i]);
;                     o[n] = (gt * up) * rc; }
;                 u32x4 w; w.x = pk2(o[0][0], o[0][1]); w.y = pk2(o[0][2], o[0][3]); w.z = pk2(o[1][0], o[1][1]); w.w = pk2(o[1][2], o[1][3]);
;                 *(u32x4*)(tb + lo + (unsigned)(ai * HALF + m * 16) * (DFF * 2)) = w; }
	v_pk_add_f32 v[58:59], v[58:59], 1.0 op_sel_hi:[1,0]
	v_pk_add_f32 v[64:65], v[64:65], 1.0 op_sel_hi:[1,0]
	v_pk_add_f32 v[62:63], v[62:63], 1.0 op_sel_hi:[1,0]
	v_rcp_f32_e32 v54, v54
	v_rcp_f32_e32 v55, v55
	v_rcp_f32_e32 v56, v56
	v_rcp_f32_e32 v57, v57
	v_rcp_f32_e32 v58, v58
	v_rcp_f32_e32 v59, v59
	v_rcp_f32_e32 v60, v60
	v_rcp_f32_e32 v61, v61
	v_add_f32_e32 v100, v92, v104
	v_add_f32_e32 v101, v93, v105
	v_add_f32_e32 v102, v90, v102
	v_add_f32_e32 v103, v91, v103
	v_rcp_f32_e32 v62, v62
	v_rcp_f32_e32 v63, v63
	v_rcp_f32_e32 v64, v64
	v_rcp_f32_e32 v65, v65
	v_exp_f32_e32 v96, v100
	v_exp_f32_e32 v97, v101
	v_exp_f32_e32 v98, v102
	v_exp_f32_e32 v99, v103
	v_pk_mul_f32 v[52:53], v[52:53], v[56:57]
	v_pk_mul_f32 v[50:51], v[50:51], v[54:55]
	v_pk_mul_f32 v[48:49], v[48:49], v[60:61]
	v_pk_mul_f32 v[46:47], v[46:47], v[58:59]
	v_pk_mul_f32 v[54:55], v[44:45], v[64:65]
	v_pk_mul_f32 v[56:57], v[42:43], v[62:63]
	v_cvt_pk_bf16_f32 v42, v50, v51
	v_cvt_pk_bf16_f32 v43, v52, v53
	v_cvt_pk_bf16_f32 v44, v46, v47
	v_cvt_pk_bf16_f32 v45, v48, v49
	v_pk_add_f32 v[98:99], v[98:99], 1.0 op_sel_hi:[1,0]
	global_store_dwordx4 v86, v[42:45], s[30:31]
	v_pk_fma_f32 v[40:41], v[40:41], v[94:95], v[72:73] op_sel_hi:[1,0,1]
	v_pk_fma_f32 v[38:39], v[38:39], v[94:95], v[70:71] op_sel_hi:[1,0,1]
	v_pk_add_f32 v[42:43], v[96:97], 1.0 op_sel_hi:[1,0]
	v_rcp_f32_e32 v44, v98
	v_rcp_f32_e32 v42, v42
	v_rcp_f32_e32 v43, v43
	v_rcp_f32_e32 v45, v99
	v_pk_fma_f32 v[36:37], v[36:37], v[94:95], v[68:69] op_sel_hi:[1,0,1]
	v_pk_fma_f32 v[34:35], v[34:35], v[94:95], v[66:67] op_sel_hi:[1,0,1]
	v_pk_mul_f32 v[36:37], v[40:41], v[36:37]
	v_pk_mul_f32 v[34:35], v[38:39], v[34:35]
	v_pk_mul_f32 v[38:39], v[36:37], v[44:45]
	v_pk_mul_f32 v[36:37], v[34:35], v[42:43]
	v_pk_fma_f32 v[28:29], v[28:29], v[88:89], v[76:77] op_sel_hi:[1,0,1]
	v_cvt_pk_bf16_f32 v36, v36, v37
	v_cvt_pk_bf16_f32 v37, v38, v39
	v_mul_f32_e32 v38, 0xbfb8aa3b, v88
	v_pk_fma_f32 v[42:43], v[30:31], v[38:39], v[116:117] op_sel_hi:[1,0,1]
	v_pk_mul_f32 v[40:41], v[32:33], v[38:39] op_sel_hi:[1,0]
	v_exp_f32_e32 v42, v42
	v_exp_f32_e32 v43, v43
	v_add_f32_e32 v39, v114, v40
	v_exp_f32_e32 v40, v39
	v_add_f32_e32 v39, v115, v41
	v_pk_fma_f32 v[32:33], v[32:33], v[88:89], v[80:81] op_sel_hi:[1,0,1]
	v_pk_fma_f32 v[30:31], v[30:31], v[88:89], v[78:79] op_sel_hi:[1,0,1]
	v_pk_fma_f32 v[26:27], v[26:27], v[88:89], v[74:75] op_sel_hi:[1,0,1]
	v_pk_mul_f32 v[28:29], v[32:33], v[28:29]
	v_pk_mul_f32 v[26:27], v[30:31], v[26:27]
	v_pk_fma_f32 v[30:31], v[24:25], v[38:39], v[90:91] op_sel_hi:[1,0,1]
	v_pk_fma_f32 v[32:33], v[22:23], v[38:39], v[92:93] op_sel_hi:[1,0,1]
	v_exp_f32_e32 v32, v32
	v_exp_f32_e32 v30, v30
	v_exp_f32_e32 v31, v31
	v_exp_f32_e32 v33, v33
	s_mov_b32 s2, 0x2b000
	v_add_co_u32_e32 v44, vcc, s2, v82
	v_cvt_pk_bf16_f32 v34, v56, v57
	v_cvt_pk_bf16_f32 v35, v54, v55
	v_addc_co_u32_e32 v45, vcc, 0, v83, vcc
	v_pk_add_f32 v[30:31], v[30:31], 1.0 op_sel_hi:[1,0]
	v_pk_add_f32 v[32:33], v[32:33], 1.0 op_sel_hi:[1,0]
	global_store_dwordx4 v[44:45], v[34:37], off
	v_rcp_f32_e32 v32, v32
	v_rcp_f32_e32 v33, v33
	v_pk_add_f32 v[36:37], v[42:43], 1.0 op_sel_hi:[1,0]
	v_rcp_f32_e32 v30, v30
	v_rcp_f32_e32 v31, v31
	v_rcp_f32_e32 v36, v36
	v_rcp_f32_e32 v37, v37
	v_pk_fma_f32 v[24:25], v[24:25], v[88:89], v[72:73] op_sel_hi:[1,0,1]
	v_pk_fma_f32 v[22:23], v[22:23], v[88:89], v[70:71] op_sel_hi:[1,0,1]
	v_pk_fma_f32 v[20:21], v[20:21], v[88:89], v[68:69] op_sel_hi:[1,0,1]
	v_pk_fma_f32 v[18:19], v[18:19], v[88:89], v[66:67] op_sel_hi:[1,0,1]
	v_pk_mul_f32 v[20:21], v[24:25], v[20:21]
	v_pk_mul_f32 v[18:19], v[22:23], v[18:19]
	v_pk_mul_f32 v[22:23], v[20:21], v[30:31]
	v_pk_mul_f32 v[20:21], v[18:19], v[32:33]
	v_pk_mul_f32 v[26:27], v[26:27], v[36:37]
	v_cvt_pk_bf16_f32 v20, v20, v21
	v_cvt_pk_bf16_f32 v21, v22, v23
	v_mul_f32_e32 v22, 0xbfb8aa3b, v84
	v_exp_f32_e32 v41, v39
	v_cvt_pk_bf16_f32 v18, v26, v27
	v_pk_fma_f32 v[26:27], v[14:15], v[22:23], v[116:117] op_sel_hi:[1,0,1]
	v_pk_mul_f32 v[24:25], v[16:17], v[22:23] op_sel_hi:[1,0]
	v_exp_f32_e32 v26, v26
	v_exp_f32_e32 v27, v27
	v_add_f32_e32 v23, v114, v24
	v_pk_add_f32 v[34:35], v[40:41], 1.0 op_sel_hi:[1,0]
	v_exp_f32_e32 v24, v23
	v_add_f32_e32 v23, v115, v25
	v_pk_fma_f32 v[16:17], v[16:17], v[84:85], v[80:81] op_sel_hi:[1,0,1]
	v_pk_fma_f32 v[14:15], v[14:15], v[84:85], v[78:79] op_sel_hi:[1,0,1]
	v_pk_fma_f32 v[12:13], v[12:13], v[84:85], v[76:77] op_sel_hi:[1,0,1]
	v_pk_fma_f32 v[10:11], v[10:11], v[84:85], v[74:75] op_sel_hi:[1,0,1]
	v_rcp_f32_e32 v34, v34
	v_rcp_f32_e32 v35, v35
	v_pk_mul_f32 v[10:11], v[14:15], v[10:11]
	v_pk_mul_f32 v[12:13], v[16:17], v[12:13]
	v_pk_fma_f32 v[14:15], v[8:9], v[22:23], v[90:91] op_sel_hi:[1,0,1]
	v_pk_fma_f32 v[16:17], v[6:7], v[22:23], v[92:93] op_sel_hi:[1,0,1]
	v_exp_f32_e32 v16, v16
	v_exp_f32_e32 v14, v14
	v_exp_f32_e32 v15, v15
	v_exp_f32_e32 v17, v17
	v_exp_f32_e32 v25, v23
	v_pk_mul_f32 v[28:29], v[28:29], v[34:35]
	s_mov_b32 s2, 0x56000
	v_cvt_pk_bf16_f32 v19, v28, v29
	v_add_co_u32_e32 v28, vcc, s2, v82
	v_pk_add_f32 v[14:15], v[14:15], 1.0 op_sel_hi:[1,0]
	s_nop 0
	v_addc_co_u32_e32 v29, vcc, 0, v83, vcc
	v_pk_add_f32 v[16:17], v[16:17], 1.0 op_sel_hi:[1,0]
	global_store_dwordx4 v[28:29], v[18:21], off
	v_rcp_f32_e32 v16, v16
	v_rcp_f32_e32 v17, v17
	v_pk_add_f32 v[18:19], v[24:25], 1.0 op_sel_hi:[1,0]
	v_pk_add_f32 v[20:21], v[26:27], 1.0 op_sel_hi:[1,0]
	v_rcp_f32_e32 v14, v14
	v_rcp_f32_e32 v15, v15
	v_rcp_f32_e32 v20, v20
	v_rcp_f32_e32 v21, v21
	v_rcp_f32_e32 v18, v18
	v_rcp_f32_e32 v19, v19
	v_pk_fma_f32 v[8:9], v[8:9], v[84:85], v[72:73] op_sel_hi:[1,0,1]
	v_pk_fma_f32 v[6:7], v[6:7], v[84:85], v[70:71] op_sel_hi:[1,0,1]
	v_pk_fma_f32 v[4:5], v[4:5], v[84:85], v[68:69] op_sel_hi:[1,0,1]
	v_pk_fma_f32 v[2:3], v[2:3], v[84:85], v[66:67] op_sel_hi:[1,0,1]
	v_pk_mul_f32 v[4:5], v[8:9], v[4:5]
	v_pk_mul_f32 v[2:3], v[6:7], v[2:3]
	v_pk_mul_f32 v[6:7], v[4:5], v[14:15]
	v_pk_mul_f32 v[4:5], v[2:3], v[16:17]
	v_pk_mul_f32 v[12:13], v[12:13], v[18:19]
	v_pk_mul_f32 v[10:11], v[10:11], v[20:21]
	v_cvt_pk_bf16_f32 v4, v4, v5
	v_cvt_pk_bf16_f32 v5, v6, v7
	v_add_co_u32_e32 v6, vcc, 0x81000, v82
	v_cvt_pk_bf16_f32 v2, v10, v11
	v_cvt_pk_bf16_f32 v3, v12, v13
	v_addc_co_u32_e32 v7, vcc, 0, v83, vcc
	global_store_dwordx4 v[6:7], v[2:5], off
	s_waitcnt vmcnt(0)
	s_barrier

; __device__ __forceinline__ float bflo(unsigned w) { return __uint_as_float(w << 16); }
; __device__ __forceinline__ float bfhi(unsigned w) { return __uint_as_float(w & 0xffff0000u); }
; __global__ void __launch_bounds__(NWAVES * 64, 2) fwd_kernel(Args a_param) {
;     ...
;         for (int m = gw; m < ML; m += ngw) {
;             const u32x2* hr = (const u32x2*)(U + (size_t)(MC + m) * DM) + lane; f32x4* xr = (f32x4*)(a.out + (size_t)m * DM) + lane;
;             f32x4 x[8]; float ss = 0.f;
; #pragma unroll
;             for (int j = 0; j < 8; ++j) { const u32x2 w = hr[64 * j]; x[j] = (f32x4){bflo(w.x), bfhi(w.x), bflo(w.y), bfhi(w.y)}; ss += (x[j].x * x[j].x + x[j].y * x[j].y) + (x[j].z * x[j].z + x[j].w * x[j].w); }
.LBB0_1861:
	s_waitcnt vmcnt(8)
	v_mov_b64_e32 v[36:37], v[110:111]
	v_mov_b64_e32 v[38:39], v[112:113]
	v_mov_b64_e32 v[40:41], v[114:115]
	v_mov_b64_e32 v[42:43], v[116:117]
	v_mov_b64_e32 v[52:53], v[118:119]
	v_mov_b64_e32 v[54:55], v[120:121]
	v_mov_b64_e32 v[56:57], v[122:123]
	v_mov_b64_e32 v[58:59], v[124:125]
	global_load_dwordx2 v[110:111], v[34:35], off
	global_load_dwordx2 v[112:113], v[34:35], off offset:512
	global_load_dwordx2 v[114:115], v[34:35], off offset:1024
	global_load_dwordx2 v[116:117], v[34:35], off offset:1536
	global_load_dwordx2 v[118:119], v[34:35], off offset:2048
	global_load_dwordx2 v[120:121], v[34:35], off offset:2560
	global_load_dwordx2 v[122:123], v[34:35], off offset:3072
	global_load_dwordx2 v[124:125], v[34:35], off offset:3584
	s_add_i32 s8, s8, s2
	v_lshl_add_u64 v[34:35], v[34:35], 0, s[6:7]
	s_cmp_lt_i32 s8, 0x8000
	v_lshlrev_b32_e32 v60, 16, v36
	v_and_b32_e32 v61, 0xffff0000, v36
	v_lshlrev_b32_e32 v36, 16, v37
	v_and_b32_e32 v37, 0xffff0000, v37
	v_lshlrev_b32_e32 v63, 16, v39
	v_lshlrev_b32_e32 v62, 16, v38
	v_and_b32_e32 v39, 0xffff0000, v39
	v_and_b32_e32 v38, 0xffff0000, v38
	v_and_b32_e32 v65, 0xffff0000, v40
	v_lshlrev_b32_e32 v67, 16, v42
	v_lshlrev_b32_e32 v77, 16, v58
	v_mul_f32_e32 v66, v37, v37
	v_pk_mul_f32 v[80:81], v[38:39], v[38:39]
	v_mul_f32_e32 v76, v61, v61
	v_lshlrev_b32_e32 v64, 16, v40
	v_lshlrev_b32_e32 v40, 16, v41
	v_and_b32_e32 v41, 0xffff0000, v41
	v_mov_b32_e32 v83, v67
	v_mul_f32_e32 v82, v65, v65
	v_mov_b32_e32 v94, v62
	v_mov_b32_e32 v95, v38
	v_mov_b32_e32 v38, v63
	v_pk_fma_f32 v[100:101], v[36:37], v[36:37], v[66:67] op_sel_hi:[1,1,0]
	v_pk_fma_f32 v[62:63], v[62:63], v[62:63], v[80:81]
	v_pk_fma_f32 v[80:81], v[60:61], v[60:61], v[76:77] op_sel_hi:[1,1,0]
	v_and_b32_e32 v69, 0xffff0000, v42
	v_lshlrev_b32_e32 v42, 16, v43
	v_and_b32_e32 v43, 0xffff0000, v43
	v_mul_f32_e32 v84, v41, v41
	v_mov_b32_e32 v85, v77
	v_pk_fma_f32 v[102:103], v[64:65], v[64:65], v[82:83] op_sel_hi:[1,1,0]
	v_mov_b32_e32 v66, v80
	v_mov_b32_e32 v82, v100
	v_mul_f32_e32 v91, v69, v69
	v_mul_f32_e32 v93, v42, v42
	v_mul_f32_e32 v106, v43, v43
	v_mov_b32_e32 v68, v67
	v_pk_fma_f32 v[104:105], v[40:41], v[40:41], v[84:85] op_sel_hi:[1,1,0]
	v_pk_add_f32 v[80:81], v[80:81], v[100:101]
	v_pk_add_f32 v[62:63], v[62:63], v[62:63] op_sel:[0,1] op_sel_hi:[1,0]
	v_pk_mul_f32 v[66:67], v[66:67], v[82:83]
	v_lshlrev_b32_e32 v71, 16, v53
	v_lshlrev_b32_e32 v70, 16, v52
	v_and_b32_e32 v53, 0xffff0000, v53
	v_and_b32_e32 v52, 0xffff0000, v52
	v_mov_b32_e32 v103, v93
	v_mov_b32_e32 v105, v106
	v_mov_b32_e32 v63, v91
	v_mov_b32_e32 v81, v67
	v_pk_mul_f32 v[86:87], v[52:53], v[52:53]
	v_pk_add_f32 v[82:83], v[102:103], v[104:105]
	v_pk_add_f32 v[62:63], v[80:81], v[62:63]
	v_lshlrev_b32_e32 v73, 16, v55
	v_lshlrev_b32_e32 v72, 16, v54
	v_and_b32_e32 v55, 0xffff0000, v55
	v_and_b32_e32 v54, 0xffff0000, v54
	v_mov_b32_e32 v96, v70
	v_mov_b32_e32 v97, v52
	v_mov_b32_e32 v52, v71
	v_pk_fma_f32 v[70:71], v[70:71], v[70:71], v[86:87]
	v_pk_add_f32 v[62:63], v[62:63], v[82:83]
	v_lshlrev_b32_e32 v74, 16, v56
	v_and_b32_e32 v75, 0xffff0000, v56
	v_lshlrev_b32_e32 v56, 16, v57
	v_and_b32_e32 v57, 0xffff0000, v57
	v_pk_mul_f32 v[88:89], v[54:55], v[54:55]
	v_pk_add_f32 v[70:71], v[70:71], v[70:71] op_sel:[0,1] op_sel_hi:[1,0]
	v_pk_add_f32 v[62:63], v[62:63], v[62:63] op_sel:[0,1] op_sel_hi:[1,0]
	v_and_b32_e32 v79, 0xffff0000, v58
	v_lshlrev_b32_e32 v58, 16, v59
	v_and_b32_e32 v59, 0xffff0000, v59
	v_mul_f32_e32 v90, v75, v75
	v_mul_f32_e32 v92, v57, v57
	v_mov_b32_e32 v98, v72
	v_mov_b32_e32 v99, v54
	v_mov_b32_e32 v54, v73
	v_pk_fma_f32 v[72:73], v[72:73], v[72:73], v[88:89]
	v_mov_b32_e32 v84, v70
	v_mov_b32_e32 v76, v62
	v_mul_f32_e32 v107, v79, v79
	v_mul_f32_e32 v108, v58, v58
	v_mul_f32_e32 v109, v59, v59
	v_pk_fma_f32 v[86:87], v[74:75], v[74:75], v[90:91] op_sel_hi:[1,1,0]
	v_pk_fma_f32 v[88:89], v[56:57], v[56:57], v[92:93] op_sel_hi:[1,1,0]
	v_pk_add_f32 v[72:73], v[72:73], v[72:73] op_sel:[0,1] op_sel_hi:[1,0]
	v_pk_add_f32 v[62:63], v[62:63], v[70:71]
	v_pk_mul_f32 v[66:67], v[76:77], v[84:85]
	v_mov_b32_e32 v87, v108
	v_mov_b32_e32 v89, v109
	v_mov_b32_e32 v73, v107
	v_mov_b32_e32 v63, v67
	v_pk_add_f32 v[86:87], v[86:87], v[88:89]
	v_pk_add_f32 v[62:63], v[62:63], v[72:73]
	v_mov_b32_e32 v78, v77
	v_pk_add_f32 v[62:63], v[62:63], v[86:87]
	s_nop 0
	v_add_f32_e32 v62, v62, v63
	s_waitcnt lgkmcnt(0)
; __device__ __forceinline__ float wave_sum(float v) {
; #pragma unroll
;     for (int o = 1; o < 64; o <<= 1) v += __shfl_xor(v, o);
;     return v;
; }
; __global__ void __launch_bounds__(NWAVES * 64, 2) fwd_kernel(Args a_param) {
;     ...
;             const float rstd = 1.0f / sqrtf(wave_sum(ss) * (1.0f / DM) + EPS);
; #pragma unroll
;             for (int j = 0; j < 8; ++j) xr[64 * j] = (x[j] * rstd) * gq[j];
;         }
	s_nop 1
	v_add_f32_dpp v62, v62, v62 quad_perm:[1,0,3,2] row_mask:0xf bank_mask:0xf
	s_waitcnt lgkmcnt(0)
	s_nop 1
	v_add_f32_dpp v62, v62, v62 quad_perm:[2,3,0,1] row_mask:0xf bank_mask:0xf
	s_waitcnt lgkmcnt(0)
	s_nop 1
	v_add_f32_dpp v62, v62, v62 row_half_mirror row_mask:0xf bank_mask:0xf
	s_waitcnt lgkmcnt(0)
	s_nop 1
	v_add_f32_dpp v62, v62, v62 row_mirror row_mask:0xf bank_mask:0xf
	v_mov_b32_e32 v63, v62
	s_nop 1
	v_permlane16_swap_b32 v62, v63
	s_waitcnt lgkmcnt(0)
	v_add_f32_e32 v62, v62, v63
	v_mov_b32_e32 v63, v62
	s_nop 1
	v_permlane32_swap_b32 v62, v63
	s_waitcnt lgkmcnt(0)
	v_add_f32_e32 v62, v62, v63
	v_fmamk_f32 v62, v62, 0x3a000000, v50
	v_mul_f32_e32 v63, 0x4f800000, v62
	v_cmp_gt_f32_e32 vcc, s3, v62
	s_nop 1
	v_cndmask_b32_e32 v62, v62, v63, vcc
	v_sqrt_f32_e32 v63, v62
	s_nop 0
	v_add_u32_e32 v66, -1, v63
	v_add_u32_e32 v67, 1, v63
	v_fma_f32 v70, -v66, v63, v62
	v_fma_f32 v71, -v67, v63, v62
	v_cmp_ge_f32_e64 s[0:1], 0, v70
	s_nop 1
	v_cndmask_b32_e64 v63, v63, v66, s[0:1]
	v_cmp_lt_f32_e64 s[0:1], 0, v71
	s_nop 1
	v_cndmask_b32_e64 v63, v63, v67, s[0:1]
	v_mul_f32_e32 v66, 0x37800000, v63
	v_cndmask_b32_e32 v63, v63, v66, vcc
	v_cmp_class_f32_e32 vcc, v62, v51
	s_nop 1
	v_cndmask_b32_e32 v62, v63, v62, vcc
	v_div_scale_f32 v63, s[0:1], v62, v62, 1.0
	v_rcp_f32_e32 v67, v63
	v_div_scale_f32 v66, vcc, 1.0, v62, 1.0
	v_fma_f32 v70, -v63, v67, 1.0
	v_fmac_f32_e32 v67, v70, v67
	v_mul_f32_e32 v70, v66, v67
	v_fma_f32 v71, -v63, v70, v66
	v_fmac_f32_e32 v70, v71, v67
	v_fma_f32 v63, -v63, v70, v66
	v_div_fmas_f32 v63, v63, v67, v70
	v_div_fixup_f32 v62, v63, v62, 1.0
	v_pk_mul_f32 v[60:61], v[62:63], v[60:61] op_sel_hi:[0,1]
	v_pk_mul_f32 v[36:37], v[62:63], v[36:37] op_sel_hi:[0,1]
	v_pk_mul_f32 v[66:67], v[62:63], v[94:95] op_sel_hi:[0,1]
	v_pk_mul_f32 v[70:71], v[62:63], v[38:39] op_sel_hi:[0,1]
	v_pk_mul_f32 v[64:65], v[62:63], v[64:65] op_sel_hi:[0,1]
	v_pk_mul_f32 v[72:73], v[62:63], v[40:41] op_sel_hi:[0,1]
	v_pk_mul_f32 v[68:69], v[62:63], v[68:69] op_sel_hi:[0,1]
	v_pk_mul_f32 v[76:77], v[62:63], v[42:43] op_sel_hi:[0,1]
	v_pk_mul_f32 v[80:81], v[62:63], v[96:97] op_sel_hi:[0,1]
	v_pk_mul_f32 v[82:83], v[62:63], v[52:53] op_sel_hi:[0,1]
	v_pk_mul_f32 v[84:85], v[62:63], v[98:99] op_sel_hi:[0,1]
	v_pk_mul_f32 v[86:87], v[62:63], v[54:55] op_sel_hi:[0,1]
	v_pk_mul_f32 v[74:75], v[62:63], v[74:75] op_sel_hi:[0,1]
	v_pk_mul_f32 v[88:89], v[62:63], v[56:57] op_sel_hi:[0,1]
	v_pk_mul_f32 v[78:79], v[62:63], v[78:79] op_sel_hi:[0,1]
	v_pk_mul_f32 v[90:91], v[62:63], v[58:59] op_sel_hi:[0,1]
	v_pk_mul_f32 v[38:39], v[36:37], v[2:3]
	v_pk_mul_f32 v[36:37], v[60:61], v[0:1]
	v_pk_mul_f32 v[42:43], v[70:71], v[6:7]
	v_pk_mul_f32 v[40:41], v[66:67], v[4:5]
	v_pk_mul_f32 v[54:55], v[72:73], v[10:11]
	v_pk_mul_f32 v[52:53], v[64:65], v[8:9]
	v_pk_mul_f32 v[58:59], v[76:77], v[14:15]
	v_pk_mul_f32 v[56:57], v[68:69], v[12:13]
	v_pk_mul_f32 v[62:63], v[82:83], v[18:19]
	v_pk_mul_f32 v[60:61], v[80:81], v[16:17]
	v_pk_mul_f32 v[66:67], v[86:87], v[22:23]
	v_pk_mul_f32 v[64:65], v[84:85], v[20:21]
	v_pk_mul_f32 v[70:71], v[88:89], v[26:27]
	v_pk_mul_f32 v[68:69], v[74:75], v[24:25]
	v_pk_mul_f32 v[74:75], v[90:91], v[30:31]
	v_pk_mul_f32 v[72:73], v[78:79], v[28:29]
	global_store_dwordx4 v[32:33], v[36:39], off offset:-4096
	global_store_dwordx4 v[32:33], v[40:43], off offset:-3072
	global_store_dwordx4 v[32:33], v[52:55], off offset:-2048
	global_store_dwordx4 v[32:33], v[56:59], off offset:-1024
	global_store_dwordx4 v[32:33], v[60:63], off
	global_store_dwordx4 v[32:33], v[64:67], off offset:1024
	global_store_dwordx4 v[32:33], v[68:71], off offset:2048
	global_store_dwordx4 v[32:33], v[72:75], off offset:3072
	v_lshl_add_u64 v[32:33], v[32:33], 0, s[4:5]
	s_cbranch_scc1 .LBB0_1861
